# attention boundary: canonicalising v_max removed, scalar DMA flag, row-max chain reordered (no nop window), trans-hazard pads replaced by independent neighbours, lgkmcnt wait pairs merged, M0 hazard n
# speedup vs baseline: 1.0127x; 1.0127x over previous
; template <int DQK, int DV, int NMAPS>
; __device__ __forceinline__ void attn_phase(const AttnArgs& a, unsigned char* smem) {
;     ...
;     auto iter = [&](f32x16 (&sc)[2], f32x16 (&sn)[2], const int t, const bool do_pv, const bool do_qk) {
;       constexpr int NPV = 4 * NDT, NQK = 2 * NKS, NMF = NPV + NQK;
;       dma(t + 2 < NKT, t + 2, t & 1, true, t, t & 1);
;       const float mnew = fmaxf(m, mxc);
;       const float alpha = __builtin_amdgcn_exp2f((m - mnew) * c);
;       m = mnew;
;       const float mc = mnew * c;
;       const unsigned vaddr = lds0 + 2 * KBYTES + ((t - 1) & 1) * VBYTES + vlane;
;       const unsigned char* kp = smem + ((t + 1) & 1) * KBYTES + klane;
;       constexpr int PD = 3;
;       bf16x8 fr[PD + 1], qv[3];
;       float ps0 = 0.f;
;       auto issue = [&](const int idx) {
;         if (idx < NPV) {
;           if (do_pv) {
;             const int js = idx / NDT, d = idx % NDT;
;             s16x4 lo, hi;
;             asm volatile("ds_read_b64_tr_b16 %0, %1 offset:%2" : "=v"(lo) : "v"(vaddr), "i"((js * 16) * VSB + d * 64) : "memory");
;             asm volatile("ds_read_b64_tr_b16 %0, %1 offset:%2" : "=v"(hi) : "v"(vaddr), "i"((js * 16 + 8) * VSB + d * 64) : "memory");
;             bf16x8 vf; vf[0] = lo[0]; vf[1] = lo[1]; vf[2] = lo[2]; vf[3] = lo[3]; vf[4] = hi[0]; vf[5] = hi[1]; vf[6] = hi[2]; vf[7] = hi[3];
;             fr[idx % (PD + 1)] = vf;
;           }
;         } else if (idx < NMF) {
;           if (do_qk) {
;             const int qi = idx - NPV, ks = qi >> 1, j = qi & 1;
;             fr[idx % (PD + 1)] = *(const bf16x8*)(kp + j * 32 * KSB + ks * 32);
;             if (j == 0) qv[ks % 3] = *(const bf16x8*)(qlds + ks * 1024);
;           }
;         }
;       };
; #pragma unroll
;       for (int i = 0; i < PD; ++i) issue(i);
; #pragma unroll
;       for (int i = 0; i < NMF; ++i) {
;         issue(i + PD);
;         if (i < NPV) {
;           if (do_pv) {
;             const int js = i / NDT, d = i % NDT;
;             union { unsigned u[4]; bf16x8 v; } cv;
; #pragma unroll
;             for (int k = 0; k < 4; ++k) cv.u[k] = ppu[4 * js + k];
;             int nafter = 0;
; #pragma unroll
;             for (int cc = i + 1; cc <= i + PD; ++cc) {
;               if (cc < NPV) nafter += 2;
;               else if (cc < NMF && do_qk) nafter += ((cc - NPV) & 1) ? 1 : 2;
;             }
.LBB0_157:
	v_add_f32_e32 v73, v73, v88
	v_add_f32_e32 v73, v74, v73
	v_add_f32_e32 v73, v75, v73
	v_add_f32_e32 v73, v76, v73
	v_add_f32_e32 v73, v77, v73
	s_add_u32 s0, s0, 0x60000
	v_add_f32_e32 v73, v78, v73
	s_addc_u32 s1, s1, 0
	s_add_i32 s82, s82, 2
	v_add_f32_e32 v109, v79, v73
	s_waitcnt vmcnt(0)
	s_add_u32 s72, s72, 0x40000
	v_fmac_f32_e32 v109, v110, v72
	s_waitcnt lgkmcnt(0)
	s_addc_u32 s73, s73, 0
	v_max_f32_e32 v72, v159, v165
	s_cmp_ge_u32 s87, s86
	s_barrier
	s_cbranch_scc1 .LBB0_218
.LBB0_158:
	s_add_i32 s87, s82, -1
	s_cmp_lt_u32 s87, s84
	s_cselect_b64 s[50:51], 0, -1
.LBB0_186:
	v_max_f32_e32 v142, v97, v72
	v_sub_f32_e32 v72, v97, v142
	v_mul_f32_e32 v96, 0x3e16c740, v72
	ds_read_b64_tr_b16 v[72:73], v106 offset:0
	ds_read_b64_tr_b16 v[74:75], v106 offset:0x600
	ds_read_b64_tr_b16 v[76:77], v106 offset:64
	ds_read_b64_tr_b16 v[78:79], v106 offset:0x640
	ds_read_b64_tr_b16 v[88:89], v106 offset:0xc00
	ds_read_b64_tr_b16 v[90:91], v106 offset:0x1200
	ds_read_b64_tr_b16 v[92:93], v106 offset:0xc40
	ds_read_b64_tr_b16 v[94:95], v106 offset:0x1240
	s_waitcnt lgkmcnt(4)
	v_mul_f32_e32 v97, 0x3e16c740, v142
	v_mfma_f32_32x32x16_bf16 v[16:31], v[72:75], v[84:87], v[16:31]
	v_fma_f32 v48, v48, s80, -v97
	v_exp_f32_e32 v110, v48
	ds_read_b64_tr_b16 v[72:73], v106 offset:0x1800
	ds_read_b64_tr_b16 v[74:75], v106 offset:0x1e00
	v_fma_f32 v48, v49, s80, -v97
	v_mfma_f32_32x32x16_bf16 v[0:15], v[76:79], v[84:87], v[0:15]
	v_exp_f32_e32 v111, v48
	v_fma_f32 v48, v50, s80, -v97
	v_exp_f32_e32 v112, v48
	ds_read_b64_tr_b16 v[76:77], v106 offset:0x1840
	ds_read_b64_tr_b16 v[78:79], v106 offset:0x1e40
	s_waitcnt lgkmcnt(4)
	v_fma_f32 v48, v51, s80, -v97
	v_mfma_f32_32x32x16_bf16 v[16:31], v[88:91], v[80:83], v[16:31]
	v_exp_f32_e32 v113, v48
	s_and_b64 vcc, exec, s[40:41]
	s_cbranch_vccnz .LBB0_162
	s_and_b64 vcc, exec, s[50:51]
	s_cbranch_vccnz .LBB0_165
	s_add_i32 m0, s25, 0x3400
	s_add_u32 s74, s0, 0xfffd0000
	s_addc_u32 s75, s1, -1
	global_load_lds_dwordx4 v98, s[74:75]
	s_branch .LBB0_165

; template <int DQK, int DV, int NMAPS>
; __device__ __forceinline__ void attn_phase(const AttnArgs& a, unsigned char* smem) {
;     ...
;       auto issue = [&](const int idx) {
;         if (idx < NPV) {
;           if (do_pv) {
;             const int js = idx / NDT, d = idx % NDT;
;             s16x4 lo, hi;
;             asm volatile("ds_read_b64_tr_b16 %0, %1 offset:%2" : "=v"(lo) : "v"(vaddr), "i"((js * 16) * VSB + d * 64) : "memory");
;             asm volatile("ds_read_b64_tr_b16 %0, %1 offset:%2" : "=v"(hi) : "v"(vaddr), "i"((js * 16 + 8) * VSB + d * 64) : "memory");
;             bf16x8 vf; vf[0] = lo[0]; vf[1] = lo[1]; vf[2] = lo[2]; vf[3] = lo[3]; vf[4] = hi[0]; vf[5] = hi[1]; vf[6] = hi[2]; vf[7] = hi[3];
;             fr[idx % (PD + 1)] = vf;
;           }
;         } else if (idx < NMF) {
;           if (do_qk) {
;             const int qi = idx - NPV, ks = qi >> 1, j = qi & 1;
;             fr[idx % (PD + 1)] = *(const bf16x8*)(kp + j * 32 * KSB + ks * 32);
;             if (j == 0) qv[ks % 3] = *(const bf16x8*)(qlds + ks * 1024);
;           }
;         }
;       };
; #pragma unroll
;       for (int i = 0; i < PD; ++i) issue(i);
; #pragma unroll
;       for (int i = 0; i < NMF; ++i) {
;         issue(i + PD);
;         if (i < NPV) {
;           if (do_pv) {
;             const int js = i / NDT, d = i % NDT;
;             union { unsigned u[4]; bf16x8 v; } cv;
; #pragma unroll
;             for (int k = 0; k < 4; ++k) cv.u[k] = ppu[4 * js + k];
;             int nafter = 0;
; #pragma unroll
;             for (int cc = i + 1; cc <= i + PD; ++cc) {
;               if (cc < NPV) nafter += 2;
;               else if (cc < NMF && do_qk) nafter += ((cc - NPV) & 1) ? 1 : 2;
;             }
;             bf16x8 vfr = fr[i % (PD + 1)];
;             asm volatile("s_waitcnt lgkmcnt(%1)" : "+v"(vfr) : "i"(nafter));
;             o[d] = MFMA32(vfr, cv.v, o[d]);
;           }
;         } else {
;           if (do_qk) {
;             const int qi = i - NPV, ks = qi >> 1, j = qi & 1;
;             if (ks == 0) {
;               f32x16 z;
; #pragma unroll
;               for (int q = 0; q < 16; ++q) z[q] = 0.f;
;               sn[j] = MFMA32(fr[i % (PD + 1)], qv[ks % 3], z);
;             } else sn[j] = MFMA32(fr[i % (PD + 1)], qv[ks % 3], sn[j]);
;           }
;         }
;         const int lo_v = i * 32 / NMF, hi_v = (i + 1) * 32 / NMF;
; #pragma unroll
.LBB0_165:
	ds_read_b64_tr_b16 v[48:49], v106 offset:0x2400
	ds_read_b64_tr_b16 v[50:51], v106 offset:0x2a00
	v_fma_f32 v52, v52, s80, -v97
	v_mfma_f32_32x32x16_bf16 v[0:15], v[92:95], v[80:83], v[0:15]
	v_exp_f32_e32 v114, v52
	v_fma_f32 v52, v53, s80, -v97
	v_exp_f32_e32 v115, v52
	ds_read_b64_tr_b16 v[80:81], v106 offset:0x2440
	ds_read_b64_tr_b16 v[82:83], v106 offset:0x2a40
	s_waitcnt lgkmcnt(4)
	v_fma_f32 v52, v54, s80, -v97
	v_mfma_f32_32x32x16_bf16 v[16:31], v[72:75], v[64:67], v[16:31]
	v_exp_f32_e32 v116, v52
	v_fma_f32 v52, v55, s80, -v97
	v_exp_f32_e32 v117, v52
	ds_read_b128 v[72:75], v102
	ds_read_b128 v[126:129], v105 offset:51200
	v_fma_f32 v52, v56, s80, -v97
	v_mfma_f32_32x32x16_bf16 v[0:15], v[76:79], v[64:67], v[0:15]
	v_exp_f32_e32 v118, v52
	ds_read_b128 v[64:67], v102 offset:6656
	s_waitcnt lgkmcnt(5)
	v_mfma_f32_32x32x16_bf16 v[16:31], v[48:51], v[68:71], v[16:31]
	v_fma_f32 v48, v57, s80, -v97
	v_exp_f32_e32 v119, v48
	v_fma_f32 v48, v58, s80, -v97
	v_exp_f32_e32 v120, v48
	s_and_b64 vcc, exec, s[26:27]
	s_cbranch_vccz .LBB0_169
	s_and_b64 vcc, exec, s[50:51]
	s_cbranch_vccnz .LBB0_172
	s_add_i32 m0, s29, 0x3400
	s_add_u32 s74, s0, 0xfffd0000
	s_addc_u32 s75, s1, -1
	global_load_lds_dwordx4 v99, s[74:75]
	s_branch .LBB0_172

; template <int DQK, int DV, int NMAPS>
; __device__ __forceinline__ void attn_phase(const AttnArgs& a, unsigned char* smem) {
;     ...
;       auto issue = [&](const int idx) {
;         if (idx < NPV) {
;           if (do_pv) {
;             const int js = idx / NDT, d = idx % NDT;
;             s16x4 lo, hi;
;             asm volatile("ds_read_b64_tr_b16 %0, %1 offset:%2" : "=v"(lo) : "v"(vaddr), "i"((js * 16) * VSB + d * 64) : "memory");
;             asm volatile("ds_read_b64_tr_b16 %0, %1 offset:%2" : "=v"(hi) : "v"(vaddr), "i"((js * 16 + 8) * VSB + d * 64) : "memory");
;             bf16x8 vf; vf[0] = lo[0]; vf[1] = lo[1]; vf[2] = lo[2]; vf[3] = lo[3]; vf[4] = hi[0]; vf[5] = hi[1]; vf[6] = hi[2]; vf[7] = hi[3];
;             fr[idx % (PD + 1)] = vf;
;           }
;         } else if (idx < NMF) {
;           if (do_qk) {
;             const int qi = idx - NPV, ks = qi >> 1, j = qi & 1;
;             fr[idx % (PD + 1)] = *(const bf16x8*)(kp + j * 32 * KSB + ks * 32);
;             if (j == 0) qv[ks % 3] = *(const bf16x8*)(qlds + ks * 1024);
;           }
;         }
;       };
; #pragma unroll
;       for (int i = 0; i < PD; ++i) issue(i);
; #pragma unroll
;       for (int i = 0; i < NMF; ++i) {
;         issue(i + PD);
;         if (i < NPV) {
;           if (do_pv) {
;             const int js = i / NDT, d = i % NDT;
;             union { unsigned u[4]; bf16x8 v; } cv;
; #pragma unroll
;             for (int k = 0; k < 4; ++k) cv.u[k] = ppu[4 * js + k];
;             int nafter = 0;
; #pragma unroll
;             for (int cc = i + 1; cc <= i + PD; ++cc) {
;               if (cc < NPV) nafter += 2;
;               else if (cc < NMF && do_qk) nafter += ((cc - NPV) & 1) ? 1 : 2;
;             }
;             bf16x8 vfr = fr[i % (PD + 1)];
;             asm volatile("s_waitcnt lgkmcnt(%1)" : "+v"(vfr) : "i"(nafter));
;             o[d] = MFMA32(vfr, cv.v, o[d]);
;           }
;         } else {
;           if (do_qk) {
;             const int qi = i - NPV, ks = qi >> 1, j = qi & 1;
;             if (ks == 0) {
;               f32x16 z;
; #pragma unroll
;               for (int q = 0; q < 16; ++q) z[q] = 0.f;
;               sn[j] = MFMA32(fr[i % (PD + 1)], qv[ks % 3], z);
;             } else sn[j] = MFMA32(fr[i % (PD + 1)], qv[ks % 3], sn[j]);
;           }
;         }
;         const int lo_v = i * 32 / NMF, hi_v = (i + 1) * 32 / NMF;
; #pragma unroll
.LBB0_172:
	ds_read_b128 v[130:133], v102 offset:32
	ds_read_b128 v[134:137], v105 offset:52224
	s_waitcnt lgkmcnt(5)
	v_fma_f32 v48, v59, s80, -v97
	v_mfma_f32_32x32x16_bf16 v[0:15], v[80:83], v[68:71], v[0:15]
	v_exp_f32_e32 v121, v48
	s_waitcnt lgkmcnt(3)
	v_mfma_f32_32x32x16_bf16 v[80:95], v[72:75], v[126:129], 0
	v_fma_f32 v48, v60, s80, -v97
	v_exp_f32_e32 v122, v48
	v_fma_f32 v48, v61, s80, -v97
	ds_read_b128 v[56:59], v102 offset:6688
	v_exp_f32_e32 v123, v48
	v_cvt_pk_bf16_f32 v52, v110, v111
	v_cvt_pk_bf16_f32 v53, v112, v113
	v_cvt_pk_bf16_f32 v54, v114, v115
	v_cvt_pk_bf16_f32 v55, v116, v117
	v_cvt_pk_bf16_f32 v48, v118, v119
	v_cvt_pk_bf16_f32 v49, v120, v121
	v_cvt_pk_bf16_f32 v50, v122, v123
	s_waitcnt lgkmcnt(3)
	v_mfma_f32_32x32x16_bf16 v[64:79], v[64:67], v[126:129], 0
	v_fma_f32 v51, v62, s80, -v97
	ds_read_b128 v[138:141], v102 offset:64
	ds_read_b128 v[144:147], v105 offset:53248
	v_exp_f32_e32 v124, v51
	v_fma_f32 v51, v63, s80, -v97
	v_exp_f32_e32 v125, v51
	s_waitcnt lgkmcnt(3)
	v_cvt_pk_bf16_f32 v51, v124, v125
	v_mfma_f32_32x32x16_bf16 v[80:95], v[130:133], v[134:137], v[80:95]
	v_fma_f32 v32, v32, s80, -v97
	ds_read_b128 v[60:63], v102 offset:6720
	v_exp_f32_e32 v126, v32
	s_and_b64 vcc, exec, s[30:31]
	s_cbranch_vccz .LBB0_176
	s_and_b64 vcc, exec, s[50:51]
	s_cbranch_vccnz .LBB0_179
	s_add_i32 m0, s33, 0x3400
	s_add_u32 s74, s0, 0xfffd0000
	s_addc_u32 s75, s1, -1
	global_load_lds_dwordx4 v100, s[74:75]
	s_branch .LBB0_179

; template <int DQK, int DV, int NMAPS>
; __device__ __forceinline__ void attn_phase(const AttnArgs& a, unsigned char* smem) {
;     ...
;       auto issue = [&](const int idx) {
;         if (idx < NPV) {
;           if (do_pv) {
;             const int js = idx / NDT, d = idx % NDT;
;             s16x4 lo, hi;
;             asm volatile("ds_read_b64_tr_b16 %0, %1 offset:%2" : "=v"(lo) : "v"(vaddr), "i"((js * 16) * VSB + d * 64) : "memory");
;             asm volatile("ds_read_b64_tr_b16 %0, %1 offset:%2" : "=v"(hi) : "v"(vaddr), "i"((js * 16 + 8) * VSB + d * 64) : "memory");
;             bf16x8 vf; vf[0] = lo[0]; vf[1] = lo[1]; vf[2] = lo[2]; vf[3] = lo[3]; vf[4] = hi[0]; vf[5] = hi[1]; vf[6] = hi[2]; vf[7] = hi[3];
;             fr[idx % (PD + 1)] = vf;
;           }
;         } else if (idx < NMF) {
;           if (do_qk) {
;             const int qi = idx - NPV, ks = qi >> 1, j = qi & 1;
;             fr[idx % (PD + 1)] = *(const bf16x8*)(kp + j * 32 * KSB + ks * 32);
;             if (j == 0) qv[ks % 3] = *(const bf16x8*)(qlds + ks * 1024);
;           }
;         }
;       };
; #pragma unroll
;       for (int i = 0; i < PD; ++i) issue(i);
; #pragma unroll
;       for (int i = 0; i < NMF; ++i) {
;         issue(i + PD);
;         if (i < NPV) {
;           if (do_pv) {
;             const int js = i / NDT, d = i % NDT;
;             union { unsigned u[4]; bf16x8 v; } cv;
; #pragma unroll
;             for (int k = 0; k < 4; ++k) cv.u[k] = ppu[4 * js + k];
;             int nafter = 0;
; #pragma unroll
;             for (int cc = i + 1; cc <= i + PD; ++cc) {
;               if (cc < NPV) nafter += 2;
;               else if (cc < NMF && do_qk) nafter += ((cc - NPV) & 1) ? 1 : 2;
;             }
;             bf16x8 vfr = fr[i % (PD + 1)];
;             asm volatile("s_waitcnt lgkmcnt(%1)" : "+v"(vfr) : "i"(nafter));
;             o[d] = MFMA32(vfr, cv.v, o[d]);
;           }
;         } else {
;           if (do_qk) {
;             const int qi = i - NPV, ks = qi >> 1, j = qi & 1;
;             if (ks == 0) {
;               f32x16 z;
; #pragma unroll
;               for (int q = 0; q < 16; ++q) z[q] = 0.f;
;               sn[j] = MFMA32(fr[i % (PD + 1)], qv[ks % 3], z);
;             } else sn[j] = MFMA32(fr[i % (PD + 1)], qv[ks % 3], sn[j]);
;           }
;         }
;         const int lo_v = i * 32 / NMF, hi_v = (i + 1) * 32 / NMF;
; #pragma unroll
.LBB0_179:
	s_waitcnt lgkmcnt(3)
	v_mfma_f32_32x32x16_bf16 v[64:79], v[56:59], v[134:137], v[64:79]
	v_fma_f32 v32, v33, s80, -v97
	ds_read_b128 v[148:151], v102 offset:96
	ds_read_b128 v[152:155], v105 offset:54272
	v_exp_f32_e32 v127, v32
	v_fma_f32 v32, v34, s80, -v97
	v_exp_f32_e32 v128, v32
	v_cvt_pk_bf16_f32 v32, v126, v127
	s_waitcnt lgkmcnt(3)
	v_mfma_f32_32x32x16_bf16 v[80:95], v[138:141], v[144:147], v[80:95]
	v_fma_f32 v33, v35, s80, -v97
	ds_read_b128 v[56:59], v102 offset:6752
	v_exp_f32_e32 v129, v33
	s_waitcnt lgkmcnt(3)
	v_cvt_pk_bf16_f32 v33, v128, v129
	v_mfma_f32_32x32x16_bf16 v[64:79], v[60:63], v[144:147], v[64:79]
	v_fma_f32 v34, v36, s80, -v97
	ds_read_b128 v[136:139], v102 offset:128
	ds_read_b128 v[156:159], v105 offset:55296
	v_exp_f32_e32 v130, v34
	v_fma_f32 v34, v37, s80, -v97
	v_exp_f32_e32 v131, v34
	s_waitcnt lgkmcnt(3)
	v_cvt_pk_bf16_f32 v34, v130, v131
	v_mfma_f32_32x32x16_bf16 v[80:95], v[148:151], v[152:155], v[80:95]
	v_fma_f32 v35, v38, s80, -v97
	v_exp_f32_e32 v132, v35
	v_fma_f32 v35, v39, s80, -v97
	ds_read_b128 v[60:63], v102 offset:6784
	v_exp_f32_e32 v133, v35
	s_and_b64 vcc, exec, s[34:35]
	v_cvt_pk_bf16_f32 v35, v132, v133
	s_cbranch_vccz .LBB0_183
	s_and_b64 vcc, exec, s[50:51]
	s_cbranch_vccnz .Lattn_mlaA_end
	s_add_i32 m0, s76, 0x3400
	s_add_u32 s50, s0, 0xfffd0000
	s_addc_u32 s51, s1, -1
	global_load_lds_dwordx4 v101, s[50:51]
	s_branch .Lattn_mlaA_end

; __device__ __forceinline__ unsigned pack2(float a, float b) { unsigned r; asm("s_nop 1\n\tv_cvt_pk_bf16_f32 %0, %1, %2" : "=v"(r) : "v"(a), "v"(b)); return r; }
; #define MX3(a_, b_, c_) __builtin_fmaxf(__builtin_fmaxf((a_), (b_)), (c_))
; template <int DQK, int DV, int NMAPS>
; __device__ __forceinline__ void attn_phase(const AttnArgs& a, unsigned char* smem) {
;     ...
;     auto rowmax = [&](const f32x16 (&sx)[2]) -> float {
;     ...
;       float mx = MX3(sx[0][0], sx[1][0], sx[0][1]);
;       mx = MX3(mx, sx[1][1], sx[0][2]);
; #pragma unroll
;       for (int q = 2; q < 15; ++q) mx = MX3(mx, sx[1][q], sx[0][q + 1]);
;       mx = __builtin_fmaxf(mx, sx[1][15]);
;     ...
;       return __builtin_fmaxf(mx, __shfl_xor(mx, 32));
;     };
;     ...
;         const int lo_v = i * 32 / NMF, hi_v = (i + 1) * 32 / NMF;
; #pragma unroll
;         for (int v = lo_v; v < hi_v; ++v) {
;           const float pvv = __builtin_amdgcn_exp2f(sc[v >> 4][v & 15] * c - mc);
;           sc[v >> 4][v & 15] = pvv;
;           ps0 += pvv;
;         }
;         if (i >= NPV) {
;           const int plo = (i == NPV) ? 0 : (lo_v >> 1), phi = hi_v >> 1;
; #pragma unroll
;           for (int pi = plo; pi < phi; ++pi) ppu[pi] = pack2(sc[(2 * pi) >> 4][(2 * pi) & 15], sc[(2 * pi + 1) >> 4][(2 * pi + 1) & 15]);
;         }
;         __builtin_amdgcn_sched_barrier(0);
;       }
;       l = l * alpha + ps0;
;       if (do_qk) mxc = rowmax(sn);
;       if (__any(alpha < 1.f)) {
; #pragma unroll
;         for (int d = 0; d < NDT; ++d)
; #pragma unroll
;           for (int q = 0; q < 16; ++q) o[d][q] *= alpha;
;       }
;       asm volatile("s_waitcnt vmcnt(0)" ::: "memory");
;       __syncthreads();
.Lattn_mlaA_end:
	s_waitcnt lgkmcnt(3)
	v_mfma_f32_32x32x16_bf16 v[64:79], v[56:59], v[152:155], v[64:79]
	ds_read_b128 v[144:147], v102 offset:160
	ds_read_b128 v[148:151], v105 offset:56320
	v_fma_f32 v36, v40, s80, -v97
	v_exp_f32_e32 v134, v36
	s_waitcnt lgkmcnt(3)
	v_mfma_f32_32x32x16_bf16 v[80:95], v[136:139], v[156:159], v[80:95]
	v_fma_f32 v36, v41, s80, -v97
	v_exp_f32_e32 v135, v36
	v_fma_f32 v36, v42, s80, -v97
	ds_read_b128 v[56:59], v102 offset:6816
	v_exp_f32_e32 v136, v36
	v_cvt_pk_bf16_f32 v36, v134, v135
	s_waitcnt lgkmcnt(3)
	v_mfma_f32_32x32x16_bf16 v[64:79], v[60:63], v[156:159], v[64:79]
	v_fma_f32 v37, v43, s80, -v97
	v_exp_f32_e32 v137, v37
	s_waitcnt lgkmcnt(1)
	v_cvt_pk_bf16_f32 v37, v136, v137
	v_mfma_f32_32x32x16_bf16 v[80:95], v[144:147], v[148:151], v[80:95]
	v_fma_f32 v38, v44, s80, -v97
	v_exp_f32_e32 v138, v38
	v_fma_f32 v38, v45, s80, -v97
	v_exp_f32_e32 v139, v38
	s_waitcnt lgkmcnt(0)
	v_cvt_pk_bf16_f32 v38, v138, v139
	v_mfma_f32_32x32x16_bf16 v[64:79], v[56:59], v[148:151], v[64:79]
	v_fma_f32 v39, v46, s80, -v97
	v_exp_f32_e32 v140, v39
	v_fma_f32 v39, v47, s80, -v97
	v_exp_f32_e32 v141, v39
	v_exp_f32_e32 v96, v96
	v_cvt_pk_bf16_f32 v39, v140, v141
	v_max3_f32 v40, v80, v81, v82
	v_max3_f32 v40, v40, v83, v84
	v_max3_f32 v40, v40, v85, v86
	v_max3_f32 v40, v40, v87, v88
	v_max3_f32 v40, v40, v89, v90
	v_max3_f32 v40, v40, v91, v92
	v_max3_f32 v40, v40, v93, v94
	v_max3_f32 v40, v40, v95, v64
	v_max3_f32 v40, v40, v65, v66
	v_max3_f32 v40, v40, v67, v68
	v_max3_f32 v40, v40, v69, v70
	v_max3_f32 v40, v40, v71, v72
	v_max3_f32 v40, v40, v73, v74
	v_max3_f32 v40, v40, v75, v76
	v_max3_f32 v40, v40, v77, v78
	v_max_f32_e32 v40, v40, v79
	ds_bpermute_b32 v41, v108, v40
	v_cmp_gt_f32_e32 vcc, 1.0, v96
	s_cbranch_vccz .LBB0_188
	v_pk_mul_f32 v[30:31], v[96:97], v[30:31] op_sel_hi:[0,1]
	v_pk_mul_f32 v[28:29], v[96:97], v[28:29] op_sel_hi:[0,1]
	v_pk_mul_f32 v[26:27], v[96:97], v[26:27] op_sel_hi:[0,1]
	v_pk_mul_f32 v[24:25], v[96:97], v[24:25] op_sel_hi:[0,1]
	v_pk_mul_f32 v[22:23], v[96:97], v[22:23] op_sel_hi:[0,1]
	v_pk_mul_f32 v[20:21], v[96:97], v[20:21] op_sel_hi:[0,1]
	v_pk_mul_f32 v[18:19], v[96:97], v[18:19] op_sel_hi:[0,1]
	v_pk_mul_f32 v[16:17], v[96:97], v[16:17] op_sel_hi:[0,1]
	v_pk_mul_f32 v[14:15], v[96:97], v[14:15] op_sel_hi:[0,1]
	v_pk_mul_f32 v[12:13], v[96:97], v[12:13] op_sel_hi:[0,1]
	v_pk_mul_f32 v[10:11], v[96:97], v[10:11] op_sel_hi:[0,1]
	v_pk_mul_f32 v[8:9], v[96:97], v[8:9] op_sel_hi:[0,1]
	v_pk_mul_f32 v[6:7], v[96:97], v[6:7] op_sel_hi:[0,1]
	v_pk_mul_f32 v[4:5], v[96:97], v[4:5] op_sel_hi:[0,1]
	v_pk_mul_f32 v[2:3], v[96:97], v[2:3] op_sel_hi:[0,1]
	v_pk_mul_f32 v[0:1], v[96:97], v[0:1] op_sel_hi:[0,1]
.LBB0_188:
	s_cmp_lt_u32 s82, s84
	s_waitcnt vmcnt(0)
	s_cselect_b64 s[50:51], 0, -1
	s_waitcnt lgkmcnt(0)
	s_barrier
.LBB0_216:
	v_max3_f32 v97, v142, v40, v41
	v_sub_f32_e32 v40, v142, v97
	v_mul_f32_e32 v165, 0x3e16c740, v40
	ds_read_b64_tr_b16 v[40:41], v107 offset:0
	ds_read_b64_tr_b16 v[42:43], v107 offset:0x600
	ds_read_b64_tr_b16 v[44:45], v107 offset:64
	ds_read_b64_tr_b16 v[46:47], v107 offset:0x640
	ds_read_b64_tr_b16 v[56:57], v107 offset:0xc00
	ds_read_b64_tr_b16 v[58:59], v107 offset:0x1200
	ds_read_b64_tr_b16 v[60:61], v107 offset:0xc40
	ds_read_b64_tr_b16 v[62:63], v107 offset:0x1240
	v_add_f32_e32 v110, 0, v110
	v_add_f32_e32 v110, v111, v110
	v_add_f32_e32 v110, v112, v110
	s_waitcnt lgkmcnt(4)
	v_mul_f32_e32 v167, 0x3e16c740, v97
	v_mfma_f32_32x32x16_bf16 v[16:31], v[40:43], v[52:55], v[16:31]
	v_fma_f32 v40, v80, s80, -v167
	v_exp_f32_e32 v142, v40
	ds_read_b64_tr_b16 v[40:41], v107 offset:0x1800
	ds_read_b64_tr_b16 v[42:43], v107 offset:0x1e00
	v_add_f32_e32 v110, v113, v110
	v_add_f32_e32 v110, v114, v110
	v_add_f32_e32 v110, v115, v110
	v_mfma_f32_32x32x16_bf16 v[0:15], v[44:47], v[52:55], v[0:15]
	v_fma_f32 v44, v81, s80, -v167
	v_exp_f32_e32 v143, v44
	v_fma_f32 v44, v82, s80, -v167
	v_exp_f32_e32 v144, v44
	ds_read_b64_tr_b16 v[44:45], v107 offset:0x1840
	ds_read_b64_tr_b16 v[46:47], v107 offset:0x1e40
	v_add_f32_e32 v110, v116, v110
	v_add_f32_e32 v110, v117, v110
	v_add_f32_e32 v110, v118, v110
	s_waitcnt lgkmcnt(4)
	v_fma_f32 v52, v83, s80, -v167
	v_mfma_f32_32x32x16_bf16 v[16:31], v[56:59], v[48:51], v[16:31]
	v_exp_f32_e32 v145, v52
	s_and_b64 vcc, exec, s[40:41]
	s_cbranch_vccnz .LBB0_192
	s_mov_b32 m0, s25
	s_and_b64 vcc, exec, s[50:51]
	s_cbranch_vccnz .LBB0_195
	global_load_lds_dwordx4 v98, s[0:1]
	s_branch .LBB0_195
.LBB0_192:
	s_add_i32 m0, s25, 0x3400
	s_and_b64 vcc, exec, s[42:43]
	s_cbranch_vccnz .LBB0_195
	global_load_lds_dwordx4 v98, s[72:73]
.LBB0_195:
	ds_read_b64_tr_b16 v[52:53], v107 offset:0x2400
	ds_read_b64_tr_b16 v[54:55], v107 offset:0x2a00
	v_add_f32_e32 v110, v119, v110
	v_add_f32_e32 v110, v120, v110
	v_add_f32_e32 v110, v121, v110
	v_mfma_f32_32x32x16_bf16 v[0:15], v[60:63], v[48:51], v[0:15]
	v_fma_f32 v48, v84, s80, -v167
	v_exp_f32_e32 v146, v48
	v_fma_f32 v48, v85, s80, -v167
	v_exp_f32_e32 v147, v48
	ds_read_b64_tr_b16 v[48:49], v107 offset:0x2440
	ds_read_b64_tr_b16 v[50:51], v107 offset:0x2a40
	v_add_f32_e32 v110, v122, v110
	v_add_f32_e32 v110, v123, v110
	v_add_f32_e32 v110, v124, v110
	s_waitcnt lgkmcnt(4)
	v_mfma_f32_32x32x16_bf16 v[16:31], v[40:43], v[32:35], v[16:31]
	v_fma_f32 v40, v86, s80, -v167
	v_exp_f32_e32 v148, v40
	v_fma_f32 v40, v87, s80, -v167
	v_exp_f32_e32 v149, v40
	ds_read_b128 v[40:43], v102 offset:13312
	ds_read_b128 v[150:153], v105 offset:51200
	v_add_f32_e32 v110, v125, v110
	v_add_f32_e32 v110, v126, v110
	v_add_f32_e32 v110, v127, v110
	v_mfma_f32_32x32x16_bf16 v[0:15], v[44:47], v[32:35], v[0:15]
	v_fma_f32 v32, v88, s80, -v167
	v_exp_f32_e32 v88, v32
	ds_read_b128 v[32:35], v102 offset:19968
	v_add_f32_e32 v110, v128, v110
	v_add_f32_e32 v110, v129, v110
	v_add_f32_e32 v110, v130, v110
	s_waitcnt lgkmcnt(5)
	v_fma_f32 v44, v89, s80, -v167
	v_mfma_f32_32x32x16_bf16 v[16:31], v[52:55], v[36:39], v[16:31]
	v_exp_f32_e32 v89, v44
	v_fma_f32 v44, v90, s80, -v167
	v_exp_f32_e32 v90, v44
	s_and_b64 vcc, exec, s[26:27]
	s_cbranch_vccz .LBB0_199
	s_mov_b32 m0, s29
	s_and_b64 vcc, exec, s[50:51]
	s_cbranch_vccnz .LBB0_202
	global_load_lds_dwordx4 v99, s[0:1]
	s_branch .LBB0_202
; template <int DQK, int DV, int NMAPS>
; __device__ __forceinline__ void attn_phase(const AttnArgs& a, unsigned char* smem) {
;     ...
;       auto issue = [&](const int idx) {
;         if (idx < NPV) {
;           if (do_pv) {
;             const int js = idx / NDT, d = idx % NDT;
;             s16x4 lo, hi;
;             asm volatile("ds_read_b64_tr_b16 %0, %1 offset:%2" : "=v"(lo) : "v"(vaddr), "i"((js * 16) * VSB + d * 64) : "memory");
;             asm volatile("ds_read_b64_tr_b16 %0, %1 offset:%2" : "=v"(hi) : "v"(vaddr), "i"((js * 16 + 8) * VSB + d * 64) : "memory");
;             bf16x8 vf; vf[0] = lo[0]; vf[1] = lo[1]; vf[2] = lo[2]; vf[3] = lo[3]; vf[4] = hi[0]; vf[5] = hi[1]; vf[6] = hi[2]; vf[7] = hi[3];
;             fr[idx % (PD + 1)] = vf;
;           }
;         } else if (idx < NMF) {
;           if (do_qk) {
;             const int qi = idx - NPV, ks = qi >> 1, j = qi & 1;
;             fr[idx % (PD + 1)] = *(const bf16x8*)(kp + j * 32 * KSB + ks * 32);
;             if (j == 0) qv[ks % 3] = *(const bf16x8*)(qlds + ks * 1024);
;           }
;         }
;       };
; #pragma unroll
;       for (int i = 0; i < PD; ++i) issue(i);
; #pragma unroll
;       for (int i = 0; i < NMF; ++i) {
;         issue(i + PD);
;         if (i < NPV) {
;           if (do_pv) {
;             const int js = i / NDT, d = i % NDT;
;             union { unsigned u[4]; bf16x8 v; } cv;
; #pragma unroll
;             for (int k = 0; k < 4; ++k) cv.u[k] = ppu[4 * js + k];
;             int nafter = 0;
; #pragma unroll
;             for (int cc = i + 1; cc <= i + PD; ++cc) {
;               if (cc < NPV) nafter += 2;
;               else if (cc < NMF && do_qk) nafter += ((cc - NPV) & 1) ? 1 : 2;
;             }
;             bf16x8 vfr = fr[i % (PD + 1)];
;             asm volatile("s_waitcnt lgkmcnt(%1)" : "+v"(vfr) : "i"(nafter));
;             o[d] = MFMA32(vfr, cv.v, o[d]);
;           }
;         } else {
;           if (do_qk) {
;             const int qi = i - NPV, ks = qi >> 1, j = qi & 1;
;             if (ks == 0) {
;               f32x16 z;
; #pragma unroll
;               for (int q = 0; q < 16; ++q) z[q] = 0.f;
;               sn[j] = MFMA32(fr[i % (PD + 1)], qv[ks % 3], z);
;             } else sn[j] = MFMA32(fr[i % (PD + 1)], qv[ks % 3], sn[j]);
;           }
;         }
;         const int lo_v = i * 32 / NMF, hi_v = (i + 1) * 32 / NMF;
; #pragma unroll
.LBB0_199:
	s_add_i32 m0, s29, 0x3400
	s_and_b64 vcc, exec, s[44:45]
	s_cbranch_vccnz .LBB0_202
	global_load_lds_dwordx4 v99, s[72:73]
.LBB0_202:
	ds_read_b128 v[154:157], v102 offset:13344
	ds_read_b128 v[168:171], v105 offset:52224
	v_add_f32_e32 v110, v131, v110
	v_add_f32_e32 v110, v132, v110
	v_add_f32_e32 v110, v133, v110
	s_waitcnt lgkmcnt(5)
	v_mfma_f32_32x32x16_bf16 v[0:15], v[48:51], v[36:39], v[0:15]
	v_fma_f32 v36, v91, s80, -v167
	v_exp_f32_e32 v91, v36
	v_add_f32_e32 v110, v134, v110
	v_add_f32_e32 v110, v135, v110
	v_add_f32_e32 v110, v136, v110
	s_waitcnt lgkmcnt(3)
	v_mfma_f32_32x32x16_bf16 v[48:63], v[40:43], v[150:153], 0
	v_fma_f32 v36, v92, s80, -v167
	v_exp_f32_e32 v92, v36
	v_fma_f32 v36, v93, s80, -v167
	ds_read_b128 v[172:175], v102 offset:20000
	v_exp_f32_e32 v93, v36
	v_cvt_pk_bf16_f32 v84, v142, v143
	v_cvt_pk_bf16_f32 v85, v144, v145
	v_cvt_pk_bf16_f32 v86, v146, v147
	v_cvt_pk_bf16_f32 v87, v148, v149
	v_cvt_pk_bf16_f32 v80, v88, v89
	v_cvt_pk_bf16_f32 v81, v90, v91
	v_cvt_pk_bf16_f32 v82, v92, v93
	v_fma_f32 v36, v94, s80, -v167
	v_exp_f32_e32 v94, v36
	v_fma_f32 v36, v95, s80, -v167
	v_exp_f32_e32 v95, v36
	v_add_f32_e32 v110, v137, v110
	v_add_f32_e32 v110, v138, v110
	v_add_f32_e32 v110, v139, v110
	s_waitcnt lgkmcnt(3)
	v_mfma_f32_32x32x16_bf16 v[32:47], v[32:35], v[150:153], 0
	ds_read_b128 v[176:179], v102 offset:13376
	ds_read_b128 v[180:183], v105 offset:53248
	v_cvt_pk_bf16_f32 v83, v94, v95
	v_add_f32_e32 v110, v140, v110
	v_add_f32_e32 v110, v141, v110
	v_fmac_f32_e32 v110, v109, v96
	s_waitcnt lgkmcnt(3)
	v_mfma_f32_32x32x16_bf16 v[48:63], v[154:157], v[168:171], v[48:63]
	v_fma_f32 v64, v64, s80, -v167
	ds_read_b128 v[206:209], v102 offset:20032
	v_exp_f32_e32 v150, v64
	s_and_b64 vcc, exec, s[30:31]
	s_cbranch_vccz .LBB0_206
	s_mov_b32 m0, s33
	s_and_b64 vcc, exec, s[50:51]
	s_cbranch_vccnz .LBB0_209
	global_load_lds_dwordx4 v100, s[0:1]
	s_branch .LBB0_209
.LBB0_206:
	s_add_i32 m0, s33, 0x3400
	s_and_b64 vcc, exec, s[46:47]
	s_cbranch_vccnz .LBB0_209
	global_load_lds_dwordx4 v100, s[72:73]
.LBB0_209:
	v_add_f32_e32 v96, 0, v142
	v_add_f32_e32 v96, v143, v96
	v_add_f32_e32 v96, v144, v96
	s_waitcnt lgkmcnt(3)
	v_mfma_f32_32x32x16_bf16 v[32:47], v[172:175], v[168:171], v[32:47]
	v_fma_f32 v64, v65, s80, -v167
	ds_read_b128 v[156:159], v102 offset:13408
	ds_read_b128 v[210:213], v105 offset:54272
	v_exp_f32_e32 v151, v64
	v_fma_f32 v64, v66, s80, -v167
	v_exp_f32_e32 v152, v64
	v_cvt_pk_bf16_f32 v64, v150, v151
	v_add_f32_e32 v96, v145, v96
	v_add_f32_e32 v96, v146, v96
	v_add_f32_e32 v96, v147, v96
	s_waitcnt lgkmcnt(3)
	v_mfma_f32_32x32x16_bf16 v[48:63], v[176:179], v[180:183], v[48:63]
	v_fma_f32 v65, v67, s80, -v167
	ds_read_b128 v[168:171], v102 offset:20064
	v_exp_f32_e32 v153, v65
	v_add_f32_e32 v96, v148, v96
	v_cvt_pk_bf16_f32 v65, v152, v153
	v_add_f32_e32 v96, v149, v96
	v_add_f32_e32 v88, v88, v96
	s_waitcnt lgkmcnt(3)
	v_mfma_f32_32x32x16_bf16 v[32:47], v[206:209], v[180:183], v[32:47]
	v_fma_f32 v66, v68, s80, -v167
	ds_read_b128 v[172:175], v102 offset:13440
	ds_read_b128 v[176:179], v105 offset:55296
	v_exp_f32_e32 v154, v66
	v_fma_f32 v66, v69, s80, -v167
	v_exp_f32_e32 v155, v66
	v_add_f32_e32 v88, v89, v88
	v_cvt_pk_bf16_f32 v66, v154, v155
	v_add_f32_e32 v88, v90, v88
	v_add_f32_e32 v88, v91, v88
	s_waitcnt lgkmcnt(3)
	v_mfma_f32_32x32x16_bf16 v[48:63], v[156:159], v[210:213], v[48:63]
	v_fma_f32 v67, v70, s80, -v167
	v_exp_f32_e32 v156, v67
	v_fma_f32 v67, v71, s80, -v167
	ds_read_b128 v[180:183], v102 offset:20096
	v_exp_f32_e32 v157, v67
	s_and_b64 vcc, exec, s[34:35]
	v_cvt_pk_bf16_f32 v67, v156, v157
	s_cbranch_vccz .LBB0_213
	s_mov_b32 m0, s76
	s_and_b64 vcc, exec, s[50:51]
	s_cbranch_vccnz .Lattn_mlaB_end
	global_load_lds_dwordx4 v101, s[0:1]
	s_branch .Lattn_mlaB_end
; __device__ __forceinline__ unsigned pack2(float a, float b) { unsigned r; asm("s_nop 1\n\tv_cvt_pk_bf16_f32 %0, %1, %2" : "=v"(r) : "v"(a), "v"(b)); return r; }
; #define MX3(a_, b_, c_) __builtin_fmaxf(__builtin_fmaxf((a_), (b_)), (c_))
; template <int DQK, int DV, int NMAPS>
; __device__ __forceinline__ void attn_phase(const AttnArgs& a, unsigned char* smem) {
;     ...
;     auto rowmax = [&](const f32x16 (&sx)[2]) -> float {
;     ...
;       float mx = MX3(sx[0][0], sx[1][0], sx[0][1]);
;       mx = MX3(mx, sx[1][1], sx[0][2]);
; #pragma unroll
;       for (int q = 2; q < 15; ++q) mx = MX3(mx, sx[1][q], sx[0][q + 1]);
;       mx = __builtin_fmaxf(mx, sx[1][15]);
;     ...
;       return __builtin_fmaxf(mx, __shfl_xor(mx, 32));
;     };
;     ...
;         const int lo_v = i * 32 / NMF, hi_v = (i + 1) * 32 / NMF;
; #pragma unroll
;         for (int v = lo_v; v < hi_v; ++v) {
;           const float pvv = __builtin_amdgcn_exp2f(sc[v >> 4][v & 15] * c - mc);
;           sc[v >> 4][v & 15] = pvv;
;           ps0 += pvv;
;         }
;         if (i >= NPV) {
;           const int plo = (i == NPV) ? 0 : (lo_v >> 1), phi = hi_v >> 1;
; #pragma unroll
;           for (int pi = plo; pi < phi; ++pi) ppu[pi] = pack2(sc[(2 * pi) >> 4][(2 * pi) & 15], sc[(2 * pi + 1) >> 4][(2 * pi + 1) & 15]);
;         }
;         __builtin_amdgcn_sched_barrier(0);
;       }
;       l = l * alpha + ps0;
;       if (do_qk) mxc = rowmax(sn);
;       if (__any(alpha < 1.f)) {
; #pragma unroll
;         for (int d = 0; d < NDT; ++d)
; #pragma unroll
;           for (int q = 0; q < 16; ++q) o[d][q] *= alpha;
.LBB0_213:
	s_add_i32 m0, s76, 0x3400
	s_and_b64 vcc, exec, s[48:49]
	s_cbranch_vccnz .Lattn_mlaB_end
	global_load_lds_dwordx4 v101, s[72:73]
.Lattn_mlaB_end:
	v_add_f32_e32 v88, v92, v88
	v_add_f32_e32 v88, v93, v88
	v_add_f32_e32 v88, v94, v88
	s_waitcnt lgkmcnt(3)
	v_mfma_f32_32x32x16_bf16 v[32:47], v[168:171], v[210:213], v[32:47]
	ds_read_b128 v[206:209], v102 offset:13472
	ds_read_b128 v[214:217], v105 offset:56320
	v_fma_f32 v68, v72, s80, -v167
	v_exp_f32_e32 v158, v68
	v_add_f32_e32 v88, v95, v88
	v_add_f32_e32 v88, v150, v88
	v_add_f32_e32 v88, v151, v88
	s_waitcnt lgkmcnt(3)
	v_mfma_f32_32x32x16_bf16 v[48:63], v[172:175], v[176:179], v[48:63]
	v_fma_f32 v68, v73, s80, -v167
	v_exp_f32_e32 v73, v68
	v_fma_f32 v68, v74, s80, -v167
	ds_read_b128 v[168:171], v102 offset:20128
	v_exp_f32_e32 v74, v68
	v_cvt_pk_bf16_f32 v68, v158, v73
	v_add_f32_e32 v88, v152, v88
	v_add_f32_e32 v88, v153, v88
	v_add_f32_e32 v88, v154, v88
	s_waitcnt lgkmcnt(3)
	v_mfma_f32_32x32x16_bf16 v[32:47], v[180:183], v[176:179], v[32:47]
	v_fma_f32 v69, v75, s80, -v167
	v_exp_f32_e32 v75, v69
	v_add_f32_e32 v88, v155, v88
	v_cvt_pk_bf16_f32 v69, v74, v75
	v_add_f32_e32 v88, v156, v88
	v_add_f32_e32 v88, v157, v88
	s_waitcnt lgkmcnt(1)
	v_mfma_f32_32x32x16_bf16 v[48:63], v[206:209], v[214:217], v[48:63]
	v_fma_f32 v70, v76, s80, -v167
	v_exp_f32_e32 v76, v70
	v_fma_f32 v70, v77, s80, -v167
	v_exp_f32_e32 v77, v70
	v_add_f32_e32 v88, v158, v88
	v_cvt_pk_bf16_f32 v70, v76, v77
	s_waitcnt lgkmcnt(0)
	v_mfma_f32_32x32x16_bf16 v[32:47], v[168:171], v[214:217], v[32:47]
	v_fma_f32 v71, v78, s80, -v167
	v_exp_f32_e32 v78, v71
	v_fma_f32 v71, v79, s80, -v167
	v_exp_f32_e32 v79, v71
	v_exp_f32_e32 v72, v165
	v_cvt_pk_bf16_f32 v71, v78, v79
	v_max3_f32 v159, v48, v49, v50
	v_max3_f32 v159, v159, v51, v52
	v_max3_f32 v159, v159, v53, v54
	v_max3_f32 v159, v159, v55, v56
	v_max3_f32 v159, v159, v57, v58
	v_max3_f32 v159, v159, v59, v60
	v_max3_f32 v159, v159, v61, v62
	v_max3_f32 v159, v159, v63, v32
	v_max3_f32 v159, v159, v33, v34
	v_max3_f32 v159, v159, v35, v36
	v_max3_f32 v159, v159, v37, v38
	v_max3_f32 v159, v159, v39, v40
	v_max3_f32 v159, v159, v41, v42
	v_max3_f32 v159, v159, v43, v44
	v_max3_f32 v159, v159, v45, v46
	v_max_f32_e32 v159, v159, v47
	ds_bpermute_b32 v165, v108, v159
	v_cmp_gt_f32_e32 vcc, 1.0, v72
	s_cbranch_vccz .LBB0_157
	v_pk_mul_f32 v[30:31], v[72:73], v[30:31] op_sel_hi:[0,1]
	v_pk_mul_f32 v[28:29], v[72:73], v[28:29] op_sel_hi:[0,1]
	v_pk_mul_f32 v[26:27], v[72:73], v[26:27] op_sel_hi:[0,1]
	v_pk_mul_f32 v[24:25], v[72:73], v[24:25] op_sel_hi:[0,1]
	v_pk_mul_f32 v[22:23], v[72:73], v[22:23] op_sel_hi:[0,1]
	v_pk_mul_f32 v[20:21], v[72:73], v[20:21] op_sel_hi:[0,1]
	v_pk_mul_f32 v[18:19], v[72:73], v[18:19] op_sel_hi:[0,1]
	v_pk_mul_f32 v[16:17], v[72:73], v[16:17] op_sel_hi:[0,1]
	v_pk_mul_f32 v[14:15], v[72:73], v[14:15] op_sel_hi:[0,1]
	v_pk_mul_f32 v[12:13], v[72:73], v[12:13] op_sel_hi:[0,1]
	v_pk_mul_f32 v[10:11], v[72:73], v[10:11] op_sel_hi:[0,1]
	v_pk_mul_f32 v[8:9], v[72:73], v[8:9] op_sel_hi:[0,1]
	v_pk_mul_f32 v[6:7], v[72:73], v[6:7] op_sel_hi:[0,1]
	v_pk_mul_f32 v[4:5], v[72:73], v[4:5] op_sel_hi:[0,1]
	v_pk_mul_f32 v[2:3], v[72:73], v[2:3] op_sel_hi:[0,1]
	v_pk_mul_f32 v[0:1], v[72:73], v[0:1] op_sel_hi:[0,1]
	s_branch .LBB0_157

; template <int DQK, int DV, int NMAPS>
; __device__ __forceinline__ void attn_phase(const AttnArgs& a, unsigned char* smem) {
;     ...
;     auto iter = [&](f32x16 (&sc)[2], f32x16 (&sn)[2], const int t, const bool do_pv, const bool do_qk) {
;       constexpr int NPV = 4 * NDT, NQK = 2 * NKS, NMF = NPV + NQK;
;       dma(t + 2 < NKT, t + 2, t & 1, true, t, t & 1);
;       const float mnew = fmaxf(m, mxc);
;       const float alpha = __builtin_amdgcn_exp2f((m - mnew) * c);
;       m = mnew;
;       const float mc = mnew * c;
;       const unsigned vaddr = lds0 + 2 * KBYTES + ((t - 1) & 1) * VBYTES + vlane;
;       const unsigned char* kp = smem + ((t + 1) & 1) * KBYTES + klane;
;       constexpr int PD = 3;
;       bf16x8 fr[PD + 1], qv[3];
;       float ps0 = 0.f;
;       auto issue = [&](const int idx) {
;         if (idx < NPV) {
;           if (do_pv) {
;             const int js = idx / NDT, d = idx % NDT;
;             s16x4 lo, hi;
;             asm volatile("ds_read_b64_tr_b16 %0, %1 offset:%2" : "=v"(lo) : "v"(vaddr), "i"((js * 16) * VSB + d * 64) : "memory");
;             asm volatile("ds_read_b64_tr_b16 %0, %1 offset:%2" : "=v"(hi) : "v"(vaddr), "i"((js * 16 + 8) * VSB + d * 64) : "memory");
;             bf16x8 vf; vf[0] = lo[0]; vf[1] = lo[1]; vf[2] = lo[2]; vf[3] = lo[3]; vf[4] = hi[0]; vf[5] = hi[1]; vf[6] = hi[2]; vf[7] = hi[3];
;             fr[idx % (PD + 1)] = vf;
;           }
;         } else if (idx < NMF) {
;           if (do_qk) {
;             const int qi = idx - NPV, ks = qi >> 1, j = qi & 1;
;             fr[idx % (PD + 1)] = *(const bf16x8*)(kp + j * 32 * KSB + ks * 32);
;             if (j == 0) qv[ks % 3] = *(const bf16x8*)(qlds + ks * 1024);
;           }
;         }
;       };
; #pragma unroll
;       for (int i = 0; i < PD; ++i) issue(i);
; #pragma unroll
;       for (int i = 0; i < NMF; ++i) {
;         issue(i + PD);
;         if (i < NPV) {
;           if (do_pv) {
;             const int js = i / NDT, d = i % NDT;
;             union { unsigned u[4]; bf16x8 v; } cv;
; #pragma unroll
;             for (int k = 0; k < 4; ++k) cv.u[k] = ppu[4 * js + k];
;             int nafter = 0;
; #pragma unroll
;             for (int cc = i + 1; cc <= i + PD; ++cc) {
;               if (cc < NPV) nafter += 2;
;               else if (cc < NMF && do_qk) nafter += ((cc - NPV) & 1) ? 1 : 2;
;             }
.LBB0_302:
	v_add_f32_e32 v118, v216, v118
	v_add_f32_e32 v118, v217, v118
	v_add_f32_e32 v101, v101, v118
	v_add_f32_e32 v101, v102, v101
	v_add_f32_e32 v101, v103, v101
	s_add_u32 s92, s92, 0xc0000
	v_add_f32_e32 v101, v104, v101
	s_addc_u32 s93, s93, 0
	s_add_i32 s82, s82, 2
	v_add_f32_e32 v141, v105, v101
	s_waitcnt vmcnt(0)
	s_add_u32 s94, s94, 0xc0000
	v_fmac_f32_e32 v141, v142, v100
	s_waitcnt lgkmcnt(0)
	s_addc_u32 s95, s95, 0
	v_max_f32_e32 v100, v218, v219
	s_cmp_ge_u32 s87, s86
	s_barrier
	s_cbranch_scc1 .LBB0_377
.LBB0_303:
	s_add_i32 s87, s82, -1
	s_cmp_lt_u32 s87, s84
	s_cselect_b64 s[52:53], 0, -1
.LBB0_338:
	v_max_f32_e32 v180, v127, v100
	v_sub_f32_e32 v100, v127, v180
	v_mul_f32_e32 v126, 0x3e38aa3b, v100
	ds_read_b64_tr_b16 v[100:101], v137 offset:0
	ds_read_b64_tr_b16 v[102:103], v137 offset:0xa00
	ds_read_b64_tr_b16 v[118:119], v137 offset:64
	ds_read_b64_tr_b16 v[120:121], v137 offset:0xa40
	ds_read_b64_tr_b16 v[122:123], v137 offset:0x80
	ds_read_b64_tr_b16 v[124:125], v137 offset:0xa80
	ds_read_b64_tr_b16 v[146:147], v137 offset:0xc0
	ds_read_b64_tr_b16 v[148:149], v137 offset:0xac0
	s_waitcnt lgkmcnt(4)
	v_mul_f32_e32 v127, 0x3e38aa3b, v180
	v_mfma_f32_32x32x16_bf16 v[48:63], v[100:103], v[114:117], v[48:63]
	v_fma_f32 v80, v80, s6, -v127
	v_exp_f32_e32 v142, v80
	ds_read_b64_tr_b16 v[100:101], v137 offset:0x1400
	ds_read_b64_tr_b16 v[102:103], v137 offset:0x1e00
	v_fma_f32 v80, v81, s6, -v127
	v_mfma_f32_32x32x16_bf16 v[32:47], v[118:121], v[114:117], v[32:47]
	v_exp_f32_e32 v143, v80
	ds_read_b64_tr_b16 v[118:119], v137 offset:0x1440
	ds_read_b64_tr_b16 v[120:121], v137 offset:0x1e40
	s_waitcnt lgkmcnt(4)
	v_fma_f32 v80, v82, s6, -v127
	v_mfma_f32_32x32x16_bf16 v[16:31], v[122:125], v[114:117], v[16:31]
	v_exp_f32_e32 v144, v80
	v_fma_f32 v80, v83, s6, -v127
	v_exp_f32_e32 v145, v80
	s_and_b64 vcc, exec, s[40:41]
	s_cbranch_vccnz .LBB0_307
	s_and_b64 vcc, exec, s[52:53]
	s_cbranch_vccnz .LBB0_310
	s_add_i32 m0, s25, 0x4400
	s_add_u32 s72, s92, 0xfffa0000
	s_addc_u32 s73, s93, -1
	global_load_lds_dwordx4 v132, s[72:73]
	s_branch .LBB0_310

; template <int DQK, int DV, int NMAPS>
; __device__ __forceinline__ void attn_phase(const AttnArgs& a, unsigned char* smem) {
;     ...
;       auto issue = [&](const int idx) {
;         if (idx < NPV) {
;           if (do_pv) {
;             const int js = idx / NDT, d = idx % NDT;
;             s16x4 lo, hi;
;             asm volatile("ds_read_b64_tr_b16 %0, %1 offset:%2" : "=v"(lo) : "v"(vaddr), "i"((js * 16) * VSB + d * 64) : "memory");
;             asm volatile("ds_read_b64_tr_b16 %0, %1 offset:%2" : "=v"(hi) : "v"(vaddr), "i"((js * 16 + 8) * VSB + d * 64) : "memory");
;             bf16x8 vf; vf[0] = lo[0]; vf[1] = lo[1]; vf[2] = lo[2]; vf[3] = lo[3]; vf[4] = hi[0]; vf[5] = hi[1]; vf[6] = hi[2]; vf[7] = hi[3];
;             fr[idx % (PD + 1)] = vf;
;           }
;         } else if (idx < NMF) {
;           if (do_qk) {
;             const int qi = idx - NPV, ks = qi >> 1, j = qi & 1;
;             fr[idx % (PD + 1)] = *(const bf16x8*)(kp + j * 32 * KSB + ks * 32);
;             if (j == 0) qv[ks % 3] = *(const bf16x8*)(qlds + ks * 1024);
;           }
;         }
;       };
; #pragma unroll
;       for (int i = 0; i < PD; ++i) issue(i);
; #pragma unroll
;       for (int i = 0; i < NMF; ++i) {
;         issue(i + PD);
;         if (i < NPV) {
;           if (do_pv) {
;             const int js = i / NDT, d = i % NDT;
;             union { unsigned u[4]; bf16x8 v; } cv;
; #pragma unroll
;             for (int k = 0; k < 4; ++k) cv.u[k] = ppu[4 * js + k];
;             int nafter = 0;
; #pragma unroll
;             for (int cc = i + 1; cc <= i + PD; ++cc) {
;               if (cc < NPV) nafter += 2;
;               else if (cc < NMF && do_qk) nafter += ((cc - NPV) & 1) ? 1 : 2;
;             }
;             bf16x8 vfr = fr[i % (PD + 1)];
;             asm volatile("s_waitcnt lgkmcnt(%1)" : "+v"(vfr) : "i"(nafter));
;             o[d] = MFMA32(vfr, cv.v, o[d]);
;           }
;         } else {
;           if (do_qk) {
;             const int qi = i - NPV, ks = qi >> 1, j = qi & 1;
;             if (ks == 0) {
;               f32x16 z;
; #pragma unroll
;               for (int q = 0; q < 16; ++q) z[q] = 0.f;
;               sn[j] = MFMA32(fr[i % (PD + 1)], qv[ks % 3], z);
;             } else sn[j] = MFMA32(fr[i % (PD + 1)], qv[ks % 3], sn[j]);
;           }
;         }
;         const int lo_v = i * 32 / NMF, hi_v = (i + 1) * 32 / NMF;
; #pragma unroll
.LBB0_310:
	ds_read_b64_tr_b16 v[80:81], v137 offset:0x1480
	ds_read_b64_tr_b16 v[82:83], v137 offset:0x1e80
	v_fma_f32 v84, v84, s6, -v127
	v_mfma_f32_32x32x16_bf16 v[0:15], v[146:149], v[114:117], v[0:15]
	v_exp_f32_e32 v146, v84
	ds_read_b64_tr_b16 v[114:115], v137 offset:0x14c0
	ds_read_b64_tr_b16 v[116:117], v137 offset:0x1ec0
	s_waitcnt lgkmcnt(4)
	v_fma_f32 v84, v85, s6, -v127
	v_mfma_f32_32x32x16_bf16 v[48:63], v[100:103], v[110:113], v[48:63]
	v_exp_f32_e32 v147, v84
	ds_read_b64_tr_b16 v[100:101], v137 offset:0x2800
	ds_read_b64_tr_b16 v[102:103], v137 offset:0x3200
	v_fma_f32 v84, v86, s6, -v127
	v_mfma_f32_32x32x16_bf16 v[32:47], v[118:121], v[110:113], v[32:47]
	v_exp_f32_e32 v148, v84
	v_fma_f32 v84, v87, s6, -v127
	v_exp_f32_e32 v149, v84
	s_and_b64 vcc, exec, s[36:37]
	s_cbranch_vccz .LBB0_314
	s_and_b64 vcc, exec, s[52:53]
	s_cbranch_vccnz .LBB0_317
	s_add_i32 m0, s29, 0x4400
	s_add_u32 s72, s92, 0xfffa0000
	s_addc_u32 s73, s93, -1
	global_load_lds_dwordx4 v131, s[72:73]
	s_branch .LBB0_317

; template <int DQK, int DV, int NMAPS>
; __device__ __forceinline__ void attn_phase(const AttnArgs& a, unsigned char* smem) {
;     ...
;       auto issue = [&](const int idx) {
;         if (idx < NPV) {
;           if (do_pv) {
;             const int js = idx / NDT, d = idx % NDT;
;             s16x4 lo, hi;
;             asm volatile("ds_read_b64_tr_b16 %0, %1 offset:%2" : "=v"(lo) : "v"(vaddr), "i"((js * 16) * VSB + d * 64) : "memory");
;             asm volatile("ds_read_b64_tr_b16 %0, %1 offset:%2" : "=v"(hi) : "v"(vaddr), "i"((js * 16 + 8) * VSB + d * 64) : "memory");
;             bf16x8 vf; vf[0] = lo[0]; vf[1] = lo[1]; vf[2] = lo[2]; vf[3] = lo[3]; vf[4] = hi[0]; vf[5] = hi[1]; vf[6] = hi[2]; vf[7] = hi[3];
;             fr[idx % (PD + 1)] = vf;
;           }
;         } else if (idx < NMF) {
;           if (do_qk) {
;             const int qi = idx - NPV, ks = qi >> 1, j = qi & 1;
;             fr[idx % (PD + 1)] = *(const bf16x8*)(kp + j * 32 * KSB + ks * 32);
;             if (j == 0) qv[ks % 3] = *(const bf16x8*)(qlds + ks * 1024);
;           }
;         }
;       };
; #pragma unroll
;       for (int i = 0; i < PD; ++i) issue(i);
; #pragma unroll
;       for (int i = 0; i < NMF; ++i) {
;         issue(i + PD);
;         if (i < NPV) {
;           if (do_pv) {
;             const int js = i / NDT, d = i % NDT;
;             union { unsigned u[4]; bf16x8 v; } cv;
; #pragma unroll
;             for (int k = 0; k < 4; ++k) cv.u[k] = ppu[4 * js + k];
;             int nafter = 0;
; #pragma unroll
;             for (int cc = i + 1; cc <= i + PD; ++cc) {
;               if (cc < NPV) nafter += 2;
;               else if (cc < NMF && do_qk) nafter += ((cc - NPV) & 1) ? 1 : 2;
;             }
;             bf16x8 vfr = fr[i % (PD + 1)];
;             asm volatile("s_waitcnt lgkmcnt(%1)" : "+v"(vfr) : "i"(nafter));
;             o[d] = MFMA32(vfr, cv.v, o[d]);
;           }
;         } else {
;           if (do_qk) {
;             const int qi = i - NPV, ks = qi >> 1, j = qi & 1;
;             if (ks == 0) {
;               f32x16 z;
; #pragma unroll
;               for (int q = 0; q < 16; ++q) z[q] = 0.f;
;               sn[j] = MFMA32(fr[i % (PD + 1)], qv[ks % 3], z);
;             } else sn[j] = MFMA32(fr[i % (PD + 1)], qv[ks % 3], sn[j]);
;           }
;         }
;         const int lo_v = i * 32 / NMF, hi_v = (i + 1) * 32 / NMF;
; #pragma unroll
.LBB0_317:
	ds_read_b64_tr_b16 v[84:85], v137 offset:0x2840
	ds_read_b64_tr_b16 v[86:87], v137 offset:0x3240
	s_waitcnt lgkmcnt(4)
	v_mfma_f32_32x32x16_bf16 v[16:31], v[80:83], v[110:113], v[16:31]
	v_fma_f32 v80, v88, s6, -v127
	v_exp_f32_e32 v150, v80
	ds_read_b64_tr_b16 v[80:81], v137 offset:0x2880
	ds_read_b64_tr_b16 v[82:83], v137 offset:0x3280
	v_fma_f32 v88, v89, s6, -v127
	v_mfma_f32_32x32x16_bf16 v[0:15], v[114:117], v[110:113], v[0:15]
	v_exp_f32_e32 v151, v88
	ds_read_b64_tr_b16 v[110:111], v137 offset:0x28c0
	ds_read_b64_tr_b16 v[112:113], v137 offset:0x32c0
	s_waitcnt lgkmcnt(4)
	v_fma_f32 v88, v90, s6, -v127
	v_mfma_f32_32x32x16_bf16 v[48:63], v[100:103], v[106:109], v[48:63]
	v_exp_f32_e32 v152, v88
	v_fma_f32 v88, v91, s6, -v127
	v_exp_f32_e32 v153, v88
	s_and_b64 vcc, exec, s[38:39]
	s_cbranch_vccz .LBB0_321
	s_and_b64 vcc, exec, s[52:53]
	s_cbranch_vccnz .LBB0_324
	s_add_i32 m0, s33, 0x4400
	s_add_u32 s72, s92, 0xfffa0000
	s_addc_u32 s73, s93, -1
	global_load_lds_dwordx4 v130, s[72:73]
	s_branch .LBB0_324

; template <int DQK, int DV, int NMAPS>
; __device__ __forceinline__ void attn_phase(const AttnArgs& a, unsigned char* smem) {
;     ...
;       auto issue = [&](const int idx) {
;         if (idx < NPV) {
;           if (do_pv) {
;             const int js = idx / NDT, d = idx % NDT;
;             s16x4 lo, hi;
;             asm volatile("ds_read_b64_tr_b16 %0, %1 offset:%2" : "=v"(lo) : "v"(vaddr), "i"((js * 16) * VSB + d * 64) : "memory");
;             asm volatile("ds_read_b64_tr_b16 %0, %1 offset:%2" : "=v"(hi) : "v"(vaddr), "i"((js * 16 + 8) * VSB + d * 64) : "memory");
;             bf16x8 vf; vf[0] = lo[0]; vf[1] = lo[1]; vf[2] = lo[2]; vf[3] = lo[3]; vf[4] = hi[0]; vf[5] = hi[1]; vf[6] = hi[2]; vf[7] = hi[3];
;             fr[idx % (PD + 1)] = vf;
;           }
;         } else if (idx < NMF) {
;           if (do_qk) {
;             const int qi = idx - NPV, ks = qi >> 1, j = qi & 1;
;             fr[idx % (PD + 1)] = *(const bf16x8*)(kp + j * 32 * KSB + ks * 32);
;             if (j == 0) qv[ks % 3] = *(const bf16x8*)(qlds + ks * 1024);
;           }
;         }
;       };
; #pragma unroll
;       for (int i = 0; i < PD; ++i) issue(i);
; #pragma unroll
;       for (int i = 0; i < NMF; ++i) {
;         issue(i + PD);
;         if (i < NPV) {
;           if (do_pv) {
;             const int js = i / NDT, d = i % NDT;
;             union { unsigned u[4]; bf16x8 v; } cv;
; #pragma unroll
;             for (int k = 0; k < 4; ++k) cv.u[k] = ppu[4 * js + k];
;             int nafter = 0;
; #pragma unroll
;             for (int cc = i + 1; cc <= i + PD; ++cc) {
;               if (cc < NPV) nafter += 2;
;               else if (cc < NMF && do_qk) nafter += ((cc - NPV) & 1) ? 1 : 2;
;             }
;             bf16x8 vfr = fr[i % (PD + 1)];
;             asm volatile("s_waitcnt lgkmcnt(%1)" : "+v"(vfr) : "i"(nafter));
;             o[d] = MFMA32(vfr, cv.v, o[d]);
;           }
;         } else {
;           if (do_qk) {
;             const int qi = i - NPV, ks = qi >> 1, j = qi & 1;
;             if (ks == 0) {
;               f32x16 z;
; #pragma unroll
;               for (int q = 0; q < 16; ++q) z[q] = 0.f;
;               sn[j] = MFMA32(fr[i % (PD + 1)], qv[ks % 3], z);
;             } else sn[j] = MFMA32(fr[i % (PD + 1)], qv[ks % 3], sn[j]);
;           }
;         }
;         const int lo_v = i * 32 / NMF, hi_v = (i + 1) * 32 / NMF;
; #pragma unroll
.LBB0_324:
	ds_read_b64_tr_b16 v[88:89], v137 offset:0x3c00
	ds_read_b64_tr_b16 v[90:91], v137 offset:0x4600
	v_mfma_f32_32x32x16_bf16 v[32:47], v[84:87], v[106:109], v[32:47]
	v_fma_f32 v84, v92, s6, -v127
	v_exp_f32_e32 v154, v84
	ds_read_b64_tr_b16 v[84:85], v137 offset:0x3c40
	ds_read_b64_tr_b16 v[86:87], v137 offset:0x4640
	s_waitcnt lgkmcnt(4)
	v_mfma_f32_32x32x16_bf16 v[16:31], v[80:83], v[106:109], v[16:31]
	v_fma_f32 v80, v93, s6, -v127
	v_exp_f32_e32 v155, v80
	ds_read_b64_tr_b16 v[80:81], v137 offset:0x3c80
	ds_read_b64_tr_b16 v[82:83], v137 offset:0x4680
	v_fma_f32 v92, v94, s6, -v127
	v_mfma_f32_32x32x16_bf16 v[0:15], v[110:113], v[106:109], v[0:15]
	v_exp_f32_e32 v156, v92
	v_fma_f32 v92, v95, s6, -v127
	v_exp_f32_e32 v157, v92
	s_and_b64 vcc, exec, s[54:55]
	s_cbranch_vccz .LBB0_328
	s_and_b64 vcc, exec, s[52:53]
	s_cbranch_vccnz .LBB0_331
	s_add_i32 m0, s74, 0x4400
	s_add_u32 s72, s92, 0xfffa0000
	s_addc_u32 s73, s93, -1
	global_load_lds_dwordx4 v129, s[72:73]
	s_branch .LBB0_331

; template <int DQK, int DV, int NMAPS>
; __device__ __forceinline__ void attn_phase(const AttnArgs& a, unsigned char* smem) {
;     ...
;       auto issue = [&](const int idx) {
;         if (idx < NPV) {
;           if (do_pv) {
;             const int js = idx / NDT, d = idx % NDT;
;             s16x4 lo, hi;
;             asm volatile("ds_read_b64_tr_b16 %0, %1 offset:%2" : "=v"(lo) : "v"(vaddr), "i"((js * 16) * VSB + d * 64) : "memory");
;             asm volatile("ds_read_b64_tr_b16 %0, %1 offset:%2" : "=v"(hi) : "v"(vaddr), "i"((js * 16 + 8) * VSB + d * 64) : "memory");
;             bf16x8 vf; vf[0] = lo[0]; vf[1] = lo[1]; vf[2] = lo[2]; vf[3] = lo[3]; vf[4] = hi[0]; vf[5] = hi[1]; vf[6] = hi[2]; vf[7] = hi[3];
;             fr[idx % (PD + 1)] = vf;
;           }
;         } else if (idx < NMF) {
;           if (do_qk) {
;             const int qi = idx - NPV, ks = qi >> 1, j = qi & 1;
;             fr[idx % (PD + 1)] = *(const bf16x8*)(kp + j * 32 * KSB + ks * 32);
;             if (j == 0) qv[ks % 3] = *(const bf16x8*)(qlds + ks * 1024);
;           }
;         }
;       };
; #pragma unroll
;       for (int i = 0; i < PD; ++i) issue(i);
; #pragma unroll
;       for (int i = 0; i < NMF; ++i) {
;         issue(i + PD);
;         if (i < NPV) {
;           if (do_pv) {
;             const int js = i / NDT, d = i % NDT;
;             union { unsigned u[4]; bf16x8 v; } cv;
; #pragma unroll
;             for (int k = 0; k < 4; ++k) cv.u[k] = ppu[4 * js + k];
;             int nafter = 0;
; #pragma unroll
;             for (int cc = i + 1; cc <= i + PD; ++cc) {
;               if (cc < NPV) nafter += 2;
;               else if (cc < NMF && do_qk) nafter += ((cc - NPV) & 1) ? 1 : 2;
;             }
;             bf16x8 vfr = fr[i % (PD + 1)];
;             asm volatile("s_waitcnt lgkmcnt(%1)" : "+v"(vfr) : "i"(nafter));
;             o[d] = MFMA32(vfr, cv.v, o[d]);
;           }
;         } else {
;           if (do_qk) {
;             const int qi = i - NPV, ks = qi >> 1, j = qi & 1;
;             if (ks == 0) {
;               f32x16 z;
; #pragma unroll
;               for (int q = 0; q < 16; ++q) z[q] = 0.f;
;               sn[j] = MFMA32(fr[i % (PD + 1)], qv[ks % 3], z);
;             } else sn[j] = MFMA32(fr[i % (PD + 1)], qv[ks % 3], sn[j]);
;           }
;         }
;         const int lo_v = i * 32 / NMF, hi_v = (i + 1) * 32 / NMF;
; #pragma unroll
.LBB0_331:
	ds_read_b64_tr_b16 v[92:93], v137 offset:0x3cc0
	ds_read_b64_tr_b16 v[94:95], v137 offset:0x46c0
	s_waitcnt lgkmcnt(4)
	v_fma_f32 v64, v64, s6, -v127
	v_mfma_f32_32x32x16_bf16 v[48:63], v[88:91], v[96:99], v[48:63]
	v_exp_f32_e32 v158, v64
	ds_read_b128 v[88:91], v135
	ds_read_b128 v[100:103], v139
	v_fma_f32 v64, v65, s6, -v127
	v_mfma_f32_32x32x16_bf16 v[32:47], v[84:87], v[96:99], v[32:47]
	v_exp_f32_e32 v159, v64
	ds_read_b128 v[172:175], v135 offset:8704
	s_waitcnt lgkmcnt(5)
	v_fma_f32 v64, v66, s6, -v127
	v_mfma_f32_32x32x16_bf16 v[16:31], v[80:83], v[96:99], v[16:31]
	v_exp_f32_e32 v165, v64
	v_fma_f32 v64, v67, s6, -v127
	v_exp_f32_e32 v167, v64
	s_and_b64 vcc, exec, s[88:89]
	s_cbranch_vccz .LBB0_335
	s_and_b64 vcc, exec, s[52:53]
	s_cbranch_vccnz .Lattn_daA_end
	s_add_i32 m0, s75, 0x4400
	s_add_u32 s52, s92, 0xfffa0000
	s_addc_u32 s53, s93, -1
	global_load_lds_dwordx4 v128, s[52:53]
	s_branch .Lattn_daA_end

; __device__ __forceinline__ unsigned pack2(float a, float b) { unsigned r; asm("s_nop 1\n\tv_cvt_pk_bf16_f32 %0, %1, %2" : "=v"(r) : "v"(a), "v"(b)); return r; }
; #define MX3(a_, b_, c_) __builtin_fmaxf(__builtin_fmaxf((a_), (b_)), (c_))
; template <int DQK, int DV, int NMAPS>
; __device__ __forceinline__ void attn_phase(const AttnArgs& a, unsigned char* smem) {
;     ...
;     auto rowmax = [&](const f32x16 (&sx)[2]) -> float {
;     ...
;       float mx = MX3(sx[0][0], sx[1][0], sx[0][1]);
;       mx = MX3(mx, sx[1][1], sx[0][2]);
; #pragma unroll
;       for (int q = 2; q < 15; ++q) mx = MX3(mx, sx[1][q], sx[0][q + 1]);
;       mx = __builtin_fmaxf(mx, sx[1][15]);
;     ...
;       return __builtin_fmaxf(mx, __shfl_xor(mx, 32));
;     };
;     ...
;         const int lo_v = i * 32 / NMF, hi_v = (i + 1) * 32 / NMF;
; #pragma unroll
;         for (int v = lo_v; v < hi_v; ++v) {
;           const float pvv = __builtin_amdgcn_exp2f(sc[v >> 4][v & 15] * c - mc);
;           sc[v >> 4][v & 15] = pvv;
;           ps0 += pvv;
;         }
;         if (i >= NPV) {
;           const int plo = (i == NPV) ? 0 : (lo_v >> 1), phi = hi_v >> 1;
; #pragma unroll
;           for (int pi = plo; pi < phi; ++pi) ppu[pi] = pack2(sc[(2 * pi) >> 4][(2 * pi) & 15], sc[(2 * pi + 1) >> 4][(2 * pi + 1) & 15]);
;         }
;         __builtin_amdgcn_sched_barrier(0);
;       }
;       l = l * alpha + ps0;
;       if (do_qk) mxc = rowmax(sn);
;       if (__any(alpha < 1.f)) {
; #pragma unroll
;         for (int d = 0; d < NDT; ++d)
; #pragma unroll
;           for (int q = 0; q < 16; ++q) o[d][q] *= alpha;
;       }
;       asm volatile("s_waitcnt vmcnt(0)" ::: "memory");
;       __syncthreads();
.Lattn_daA_end:
	ds_read_b128 v[64:67], v135 offset:32
	ds_read_b128 v[176:179], v139 offset:1024
	s_waitcnt lgkmcnt(5)
	v_fma_f32 v68, v68, s6, -v127
	v_mfma_f32_32x32x16_bf16 v[0:15], v[92:95], v[96:99], v[0:15]
	v_exp_f32_e32 v168, v68
	s_waitcnt lgkmcnt(3)
	v_mfma_f32_32x32x16_bf16 v[106:121], v[88:91], v[100:103], 0
	v_fma_f32 v68, v69, s6, -v127
	ds_read_b128 v[182:185], v135 offset:8736
	v_exp_f32_e32 v169, v68
	v_cvt_pk_bf16_f32 v122, v142, v143
	v_cvt_pk_bf16_f32 v123, v144, v145
	v_cvt_pk_bf16_f32 v124, v146, v147
	v_cvt_pk_bf16_f32 v125, v148, v149
	v_cvt_pk_bf16_f32 v84, v150, v151
	v_cvt_pk_bf16_f32 v85, v152, v153
	v_cvt_pk_bf16_f32 v86, v154, v155
	v_cvt_pk_bf16_f32 v87, v156, v157
	v_cvt_pk_bf16_f32 v80, v158, v159
	v_cvt_pk_bf16_f32 v81, v165, v167
	v_cvt_pk_bf16_f32 v82, v168, v169
	s_waitcnt lgkmcnt(3)
	v_mfma_f32_32x32x16_bf16 v[90:105], v[172:175], v[100:103], 0
	v_fma_f32 v68, v70, s6, -v127
	ds_read_b128 v[206:209], v135 offset:64
	ds_read_b128 v[210:213], v139 offset:2048
	v_exp_f32_e32 v170, v68
	v_fma_f32 v68, v71, s6, -v127
	v_exp_f32_e32 v171, v68
	s_waitcnt lgkmcnt(3)
	v_cvt_pk_bf16_f32 v83, v170, v171
	v_mfma_f32_32x32x16_bf16 v[106:121], v[64:67], v[176:179], v[106:121]
	ds_read_b128 v[68:71], v135 offset:8768
	v_fma_f32 v64, v72, s6, -v127
	v_exp_f32_e32 v172, v64
	s_waitcnt lgkmcnt(3)
	v_mfma_f32_32x32x16_bf16 v[90:105], v[182:185], v[176:179], v[90:105]
	ds_read_b128 v[214:217], v135 offset:96
	ds_read_b128 v[218:221], v139 offset:3072
	v_fma_f32 v64, v73, s6, -v127
	v_exp_f32_e32 v173, v64
	s_waitcnt lgkmcnt(3)
	v_cvt_pk_bf16_f32 v64, v172, v173
	v_mfma_f32_32x32x16_bf16 v[106:121], v[206:209], v[210:213], v[106:121]
	v_fma_f32 v65, v74, s6, -v127
	v_exp_f32_e32 v174, v65
	v_fma_f32 v65, v75, s6, -v127
	ds_read_b128 v[182:185], v135 offset:8800
	v_exp_f32_e32 v175, v65
	s_waitcnt lgkmcnt(3)
	v_cvt_pk_bf16_f32 v65, v174, v175
	v_mfma_f32_32x32x16_bf16 v[90:105], v[68:71], v[210:213], v[90:105]
	v_fma_f32 v66, v76, s6, -v127
	v_exp_f32_e32 v176, v66
	s_waitcnt lgkmcnt(1)
	v_mfma_f32_32x32x16_bf16 v[106:121], v[214:217], v[218:221], v[106:121]
	v_fma_f32 v66, v77, s6, -v127
	v_exp_f32_e32 v177, v66
	s_waitcnt lgkmcnt(0)
	v_cvt_pk_bf16_f32 v66, v176, v177
	v_mfma_f32_32x32x16_bf16 v[90:105], v[182:185], v[218:221], v[90:105]
	v_fma_f32 v67, v78, s6, -v127
	v_exp_f32_e32 v178, v67
	v_fma_f32 v67, v79, s6, -v127
	v_exp_f32_e32 v179, v67
	v_exp_f32_e32 v126, v126
	v_cvt_pk_bf16_f32 v67, v178, v179
	v_max3_f32 v68, v106, v107, v108
	v_max3_f32 v68, v68, v109, v110
	v_max3_f32 v68, v68, v111, v112
	v_max3_f32 v68, v68, v113, v114
	v_max3_f32 v68, v68, v115, v116
	v_max3_f32 v68, v68, v117, v118
	v_max3_f32 v68, v68, v119, v120
	v_max3_f32 v68, v68, v121, v90
	v_max3_f32 v68, v68, v91, v92
	v_max3_f32 v68, v68, v93, v94
	v_max3_f32 v68, v68, v95, v96
	v_max3_f32 v68, v68, v97, v98
	v_max3_f32 v68, v68, v99, v100
	v_max3_f32 v68, v68, v101, v102
	v_max3_f32 v68, v68, v103, v104
	v_max_f32_e32 v68, v68, v105
	ds_bpermute_b32 v69, v140, v68
	v_cmp_gt_f32_e32 vcc, 1.0, v126
	s_cbranch_vccz .LBB0_340
	v_pk_mul_f32 v[62:63], v[126:127], v[62:63] op_sel_hi:[0,1]
	v_pk_mul_f32 v[60:61], v[126:127], v[60:61] op_sel_hi:[0,1]
	v_pk_mul_f32 v[58:59], v[126:127], v[58:59] op_sel_hi:[0,1]
	v_pk_mul_f32 v[56:57], v[126:127], v[56:57] op_sel_hi:[0,1]
	v_pk_mul_f32 v[54:55], v[126:127], v[54:55] op_sel_hi:[0,1]
	v_pk_mul_f32 v[52:53], v[126:127], v[52:53] op_sel_hi:[0,1]
	v_pk_mul_f32 v[50:51], v[126:127], v[50:51] op_sel_hi:[0,1]
	v_pk_mul_f32 v[48:49], v[126:127], v[48:49] op_sel_hi:[0,1]
	v_pk_mul_f32 v[46:47], v[126:127], v[46:47] op_sel_hi:[0,1]
	v_pk_mul_f32 v[44:45], v[126:127], v[44:45] op_sel_hi:[0,1]
	v_pk_mul_f32 v[42:43], v[126:127], v[42:43] op_sel_hi:[0,1]
	v_pk_mul_f32 v[40:41], v[126:127], v[40:41] op_sel_hi:[0,1]
	v_pk_mul_f32 v[38:39], v[126:127], v[38:39] op_sel_hi:[0,1]
	v_pk_mul_f32 v[36:37], v[126:127], v[36:37] op_sel_hi:[0,1]
	v_pk_mul_f32 v[34:35], v[126:127], v[34:35] op_sel_hi:[0,1]
	v_pk_mul_f32 v[32:33], v[126:127], v[32:33] op_sel_hi:[0,1]
	v_pk_mul_f32 v[30:31], v[126:127], v[30:31] op_sel_hi:[0,1]
	v_pk_mul_f32 v[28:29], v[126:127], v[28:29] op_sel_hi:[0,1]
	v_pk_mul_f32 v[26:27], v[126:127], v[26:27] op_sel_hi:[0,1]
	v_pk_mul_f32 v[24:25], v[126:127], v[24:25] op_sel_hi:[0,1]
	v_pk_mul_f32 v[22:23], v[126:127], v[22:23] op_sel_hi:[0,1]
	v_pk_mul_f32 v[20:21], v[126:127], v[20:21] op_sel_hi:[0,1]
	v_pk_mul_f32 v[18:19], v[126:127], v[18:19] op_sel_hi:[0,1]
	v_pk_mul_f32 v[16:17], v[126:127], v[16:17] op_sel_hi:[0,1]
	v_pk_mul_f32 v[14:15], v[126:127], v[14:15] op_sel_hi:[0,1]
	v_pk_mul_f32 v[12:13], v[126:127], v[12:13] op_sel_hi:[0,1]
	v_pk_mul_f32 v[10:11], v[126:127], v[10:11] op_sel_hi:[0,1]
	v_pk_mul_f32 v[8:9], v[126:127], v[8:9] op_sel_hi:[0,1]
	v_pk_mul_f32 v[6:7], v[126:127], v[6:7] op_sel_hi:[0,1]
	v_pk_mul_f32 v[4:5], v[126:127], v[4:5] op_sel_hi:[0,1]
	v_pk_mul_f32 v[2:3], v[126:127], v[2:3] op_sel_hi:[0,1]
	v_pk_mul_f32 v[0:1], v[126:127], v[0:1] op_sel_hi:[0,1]
.LBB0_340:
	s_cmp_lt_u32 s82, s84
	s_waitcnt vmcnt(0)
	s_cselect_b64 s[52:53], 0, -1
	s_waitcnt lgkmcnt(0)
	s_barrier
; template <int DQK, int DV, int NMAPS>
; __device__ __forceinline__ void attn_phase(const AttnArgs& a, unsigned char* smem) {
;     ...
;       auto issue = [&](const int idx) {
;         if (idx < NPV) {
;           if (do_pv) {
;             const int js = idx / NDT, d = idx % NDT;
;             s16x4 lo, hi;
;             asm volatile("ds_read_b64_tr_b16 %0, %1 offset:%2" : "=v"(lo) : "v"(vaddr), "i"((js * 16) * VSB + d * 64) : "memory");
;             asm volatile("ds_read_b64_tr_b16 %0, %1 offset:%2" : "=v"(hi) : "v"(vaddr), "i"((js * 16 + 8) * VSB + d * 64) : "memory");
;             bf16x8 vf; vf[0] = lo[0]; vf[1] = lo[1]; vf[2] = lo[2]; vf[3] = lo[3]; vf[4] = hi[0]; vf[5] = hi[1]; vf[6] = hi[2]; vf[7] = hi[3];
;             fr[idx % (PD + 1)] = vf;
;           }
;         } else if (idx < NMF) {
;           if (do_qk) {
;             const int qi = idx - NPV, ks = qi >> 1, j = qi & 1;
;             fr[idx % (PD + 1)] = *(const bf16x8*)(kp + j * 32 * KSB + ks * 32);
;             if (j == 0) qv[ks % 3] = *(const bf16x8*)(qlds + ks * 1024);
;           }
;         }
;       };
; #pragma unroll
;       for (int i = 0; i < PD; ++i) issue(i);
; #pragma unroll
;       for (int i = 0; i < NMF; ++i) {
;         issue(i + PD);
;         if (i < NPV) {
;           if (do_pv) {
;             const int js = i / NDT, d = i % NDT;
;             union { unsigned u[4]; bf16x8 v; } cv;
; #pragma unroll
;             for (int k = 0; k < 4; ++k) cv.u[k] = ppu[4 * js + k];
;             int nafter = 0;
; #pragma unroll
;             for (int cc = i + 1; cc <= i + PD; ++cc) {
;               if (cc < NPV) nafter += 2;
;               else if (cc < NMF && do_qk) nafter += ((cc - NPV) & 1) ? 1 : 2;
;             }
;             bf16x8 vfr = fr[i % (PD + 1)];
;             asm volatile("s_waitcnt lgkmcnt(%1)" : "+v"(vfr) : "i"(nafter));
;             o[d] = MFMA32(vfr, cv.v, o[d]);
;           }
;         } else {
;           if (do_qk) {
;             const int qi = i - NPV, ks = qi >> 1, j = qi & 1;
;             if (ks == 0) {
;               f32x16 z;
; #pragma unroll
;               for (int q = 0; q < 16; ++q) z[q] = 0.f;
;               sn[j] = MFMA32(fr[i % (PD + 1)], qv[ks % 3], z);
;             } else sn[j] = MFMA32(fr[i % (PD + 1)], qv[ks % 3], sn[j]);
;           }
;         }
;         const int lo_v = i * 32 / NMF, hi_v = (i + 1) * 32 / NMF;
; #pragma unroll
.LBB0_375:
	v_max3_f32 v127, v180, v68, v69
	v_sub_f32_e32 v68, v180, v127
	v_mul_f32_e32 v248, 0x3e38aa3b, v68
	ds_read_b64_tr_b16 v[68:69], v138 offset:0
	ds_read_b64_tr_b16 v[70:71], v138 offset:0xa00
	ds_read_b64_tr_b16 v[72:73], v138 offset:64
	ds_read_b64_tr_b16 v[74:75], v138 offset:0xa40
	ds_read_b64_tr_b16 v[76:77], v138 offset:0x80
	ds_read_b64_tr_b16 v[78:79], v138 offset:0xa80
	ds_read_b64_tr_b16 v[206:207], v138 offset:0xc0
	ds_read_b64_tr_b16 v[208:209], v138 offset:0xac0
	v_add_f32_e32 v142, 0, v142
	v_add_f32_e32 v142, v143, v142
	v_add_f32_e32 v142, v144, v142
	s_waitcnt lgkmcnt(4)
	v_mul_f32_e32 v249, 0x3e38aa3b, v127
	v_mfma_f32_32x32x16_bf16 v[48:63], v[68:71], v[122:125], v[48:63]
	v_fma_f32 v68, v106, s6, -v249
	v_exp_f32_e32 v180, v68
	ds_read_b64_tr_b16 v[68:69], v138 offset:0x1400
	ds_read_b64_tr_b16 v[70:71], v138 offset:0x1e00
	v_add_f32_e32 v142, v145, v142
	v_add_f32_e32 v142, v146, v142
	v_add_f32_e32 v142, v147, v142
	v_mfma_f32_32x32x16_bf16 v[32:47], v[72:75], v[122:125], v[32:47]
	v_fma_f32 v72, v107, s6, -v249
	v_exp_f32_e32 v181, v72
	ds_read_b64_tr_b16 v[72:73], v138 offset:0x1440
	ds_read_b64_tr_b16 v[74:75], v138 offset:0x1e40
	v_add_f32_e32 v142, v148, v142
	v_add_f32_e32 v142, v149, v142
	v_add_f32_e32 v142, v150, v142
	s_waitcnt lgkmcnt(4)
	v_mfma_f32_32x32x16_bf16 v[16:31], v[76:79], v[122:125], v[16:31]
	v_fma_f32 v76, v108, s6, -v249
	v_exp_f32_e32 v182, v76
	v_fma_f32 v76, v109, s6, -v249
	v_exp_f32_e32 v183, v76
	s_and_b64 vcc, exec, s[40:41]
	s_cbranch_vccnz .LBB0_344
	s_mov_b32 m0, s25
	s_and_b64 vcc, exec, s[52:53]
	s_cbranch_vccnz .LBB0_347
	global_load_lds_dwordx4 v132, s[92:93]
	s_branch .LBB0_347
.LBB0_344:
	s_add_i32 m0, s25, 0x4400
	s_and_b64 vcc, exec, s[42:43]
	s_cbranch_vccnz .LBB0_347
	global_load_lds_dwordx4 v132, s[94:95]
.LBB0_347:
	ds_read_b64_tr_b16 v[76:77], v138 offset:0x1480
	ds_read_b64_tr_b16 v[78:79], v138 offset:0x1e80
	v_add_f32_e32 v142, v151, v142
	v_add_f32_e32 v142, v152, v142
	v_add_f32_e32 v142, v153, v142
	v_fma_f32 v88, v110, s6, -v249
	v_mfma_f32_32x32x16_bf16 v[0:15], v[206:209], v[122:125], v[0:15]
	v_exp_f32_e32 v122, v88
	ds_read_b64_tr_b16 v[106:107], v138 offset:0x14c0
	ds_read_b64_tr_b16 v[108:109], v138 offset:0x1ec0
	v_add_f32_e32 v142, v154, v142
	v_add_f32_e32 v142, v155, v142
	v_add_f32_e32 v142, v156, v142
	s_waitcnt lgkmcnt(4)
	v_mfma_f32_32x32x16_bf16 v[48:63], v[68:71], v[84:87], v[48:63]
	v_fma_f32 v68, v111, s6, -v249
	v_exp_f32_e32 v123, v68
	ds_read_b64_tr_b16 v[68:69], v138 offset:0x2800
	ds_read_b64_tr_b16 v[70:71], v138 offset:0x3200
	v_add_f32_e32 v142, v157, v142
	v_add_f32_e32 v142, v158, v142
	v_add_f32_e32 v142, v159, v142
	v_mfma_f32_32x32x16_bf16 v[32:47], v[72:75], v[84:87], v[32:47]
	v_fma_f32 v72, v112, s6, -v249
	v_exp_f32_e32 v124, v72
	v_fma_f32 v72, v113, s6, -v249
	v_exp_f32_e32 v125, v72
	s_and_b64 vcc, exec, s[36:37]
	s_cbranch_vccz .LBB0_351
	s_mov_b32 m0, s29
	s_and_b64 vcc, exec, s[52:53]
	s_cbranch_vccnz .LBB0_354
	global_load_lds_dwordx4 v131, s[92:93]
	s_branch .LBB0_354
.LBB0_351:
	s_add_i32 m0, s29, 0x4400
	s_and_b64 vcc, exec, s[44:45]
	s_cbranch_vccnz .LBB0_354
	global_load_lds_dwordx4 v131, s[94:95]
.LBB0_354:
	ds_read_b64_tr_b16 v[72:73], v138 offset:0x2840
	ds_read_b64_tr_b16 v[74:75], v138 offset:0x3240
	v_add_f32_e32 v142, v165, v142
	v_add_f32_e32 v142, v167, v142
	v_add_f32_e32 v142, v168, v142
	s_waitcnt lgkmcnt(4)
	v_mfma_f32_32x32x16_bf16 v[16:31], v[76:79], v[84:87], v[16:31]
	v_fma_f32 v76, v114, s6, -v249
	v_exp_f32_e32 v184, v76
	ds_read_b64_tr_b16 v[76:77], v138 offset:0x2880
	ds_read_b64_tr_b16 v[78:79], v138 offset:0x3280
	v_add_f32_e32 v142, v169, v142
	v_add_f32_e32 v142, v170, v142
	v_add_f32_e32 v142, v171, v142
	v_mfma_f32_32x32x16_bf16 v[0:15], v[106:109], v[84:87], v[0:15]
	v_fma_f32 v84, v115, s6, -v249
	v_exp_f32_e32 v185, v84
	ds_read_b64_tr_b16 v[84:85], v138 offset:0x28c0
	ds_read_b64_tr_b16 v[86:87], v138 offset:0x32c0
	v_add_f32_e32 v142, v172, v142
	v_add_f32_e32 v142, v173, v142
	v_add_f32_e32 v142, v174, v142
	s_waitcnt lgkmcnt(4)
	v_mfma_f32_32x32x16_bf16 v[48:63], v[68:71], v[80:83], v[48:63]
	v_fma_f32 v68, v116, s6, -v249
	v_exp_f32_e32 v205, v68
	v_fma_f32 v68, v117, s6, -v249
	v_exp_f32_e32 v206, v68
	s_and_b64 vcc, exec, s[38:39]
	s_cbranch_vccz .LBB0_358
	s_mov_b32 m0, s33
	s_and_b64 vcc, exec, s[52:53]
	s_cbranch_vccnz .LBB0_361
	global_load_lds_dwordx4 v130, s[92:93]
	s_branch .LBB0_361
.LBB0_358:
	s_add_i32 m0, s33, 0x4400
	s_and_b64 vcc, exec, s[46:47]
	s_cbranch_vccnz .LBB0_361
	global_load_lds_dwordx4 v130, s[94:95]
.LBB0_361:
	ds_read_b64_tr_b16 v[68:69], v138 offset:0x3c00
	ds_read_b64_tr_b16 v[70:71], v138 offset:0x4600
	v_add_f32_e32 v142, v175, v142
	v_add_f32_e32 v142, v176, v142
	v_add_f32_e32 v142, v177, v142
	v_mfma_f32_32x32x16_bf16 v[32:47], v[72:75], v[80:83], v[32:47]
	v_fma_f32 v72, v118, s6, -v249
	v_exp_f32_e32 v118, v72
	ds_read_b64_tr_b16 v[72:73], v138 offset:0x3c40
	ds_read_b64_tr_b16 v[74:75], v138 offset:0x4640
	v_add_f32_e32 v142, v178, v142
	v_add_f32_e32 v142, v179, v142
	v_fmac_f32_e32 v142, v141, v126
	s_waitcnt lgkmcnt(4)
	v_mfma_f32_32x32x16_bf16 v[16:31], v[76:79], v[80:83], v[16:31]
	v_fma_f32 v76, v119, s6, -v249
	v_exp_f32_e32 v119, v76
	ds_read_b64_tr_b16 v[76:77], v138 offset:0x3c80
	ds_read_b64_tr_b16 v[78:79], v138 offset:0x4680
	v_add_f32_e32 v126, 0, v180
	v_add_f32_e32 v126, v181, v126
	v_add_f32_e32 v126, v182, v126
	v_mfma_f32_32x32x16_bf16 v[0:15], v[84:87], v[80:83], v[0:15]
	v_fma_f32 v80, v120, s6, -v249
	v_exp_f32_e32 v120, v80
	v_fma_f32 v80, v121, s6, -v249
	v_exp_f32_e32 v121, v80
	s_and_b64 vcc, exec, s[54:55]
	s_cbranch_vccz .LBB0_365
	s_mov_b32 m0, s74
	s_and_b64 vcc, exec, s[52:53]
	s_cbranch_vccnz .LBB0_368
	global_load_lds_dwordx4 v129, s[92:93]
	s_branch .LBB0_368
; __device__ __forceinline__ unsigned pack2(float a, float b) { unsigned r; asm("s_nop 1\n\tv_cvt_pk_bf16_f32 %0, %1, %2" : "=v"(r) : "v"(a), "v"(b)); return r; }
; #define MX3(a_, b_, c_) __builtin_fmaxf(__builtin_fmaxf((a_), (b_)), (c_))
; template <int DQK, int DV, int NMAPS>
; __device__ __forceinline__ void attn_phase(const AttnArgs& a, unsigned char* smem) {
;     ...
;     auto rowmax = [&](const f32x16 (&sx)[2]) -> float {
;     ...
;       float mx = MX3(sx[0][0], sx[1][0], sx[0][1]);
;       mx = MX3(mx, sx[1][1], sx[0][2]);
; #pragma unroll
;       for (int q = 2; q < 15; ++q) mx = MX3(mx, sx[1][q], sx[0][q + 1]);
;       mx = __builtin_fmaxf(mx, sx[1][15]);
;     ...
;       return __builtin_fmaxf(mx, __shfl_xor(mx, 32));
;     };
;     ...
;         const int lo_v = i * 32 / NMF, hi_v = (i + 1) * 32 / NMF;
; #pragma unroll
;         for (int v = lo_v; v < hi_v; ++v) {
;           const float pvv = __builtin_amdgcn_exp2f(sc[v >> 4][v & 15] * c - mc);
;           sc[v >> 4][v & 15] = pvv;
;           ps0 += pvv;
;         }
;         if (i >= NPV) {
;           const int plo = (i == NPV) ? 0 : (lo_v >> 1), phi = hi_v >> 1;
; #pragma unroll
;           for (int pi = plo; pi < phi; ++pi) ppu[pi] = pack2(sc[(2 * pi) >> 4][(2 * pi) & 15], sc[(2 * pi + 1) >> 4][(2 * pi + 1) & 15]);
;         }
;         __builtin_amdgcn_sched_barrier(0);
;       }
;       l = l * alpha + ps0;
;       if (do_qk) mxc = rowmax(sn);
;       if (__any(alpha < 1.f)) {
; #pragma unroll
;         for (int d = 0; d < NDT; ++d)
; #pragma unroll
;           for (int q = 0; q < 16; ++q) o[d][q] *= alpha;
.LBB0_365:
	s_add_i32 m0, s74, 0x4400
	s_and_b64 vcc, exec, s[48:49]
	s_cbranch_vccnz .LBB0_368
	global_load_lds_dwordx4 v129, s[94:95]
.LBB0_368:
	ds_read_b64_tr_b16 v[80:81], v138 offset:0x3cc0
	ds_read_b64_tr_b16 v[82:83], v138 offset:0x46c0
	v_add_f32_e32 v126, v183, v126
	s_waitcnt lgkmcnt(4)
	v_mfma_f32_32x32x16_bf16 v[48:63], v[68:71], v[64:67], v[48:63]
	v_fma_f32 v68, v90, s6, -v249
	v_exp_f32_e32 v207, v68
	ds_read_b128 v[68:71], v135 offset:17408
	ds_read_b128 v[216:219], v139
	v_mfma_f32_32x32x16_bf16 v[32:47], v[72:75], v[64:67], v[32:47]
	v_fma_f32 v72, v91, s6, -v249
	v_exp_f32_e32 v208, v72
	ds_read_b128 v[72:75], v135 offset:26112
	s_waitcnt lgkmcnt(5)
	v_mfma_f32_32x32x16_bf16 v[16:31], v[76:79], v[64:67], v[16:31]
	v_fma_f32 v76, v92, s6, -v249
	v_exp_f32_e32 v209, v76
	v_fma_f32 v76, v93, s6, -v249
	v_exp_f32_e32 v210, v76
	s_and_b64 vcc, exec, s[88:89]
	s_cbranch_vccz .LBB0_372
	s_mov_b32 m0, s75
	s_and_b64 vcc, exec, s[52:53]
	s_cbranch_vccnz .Lattn_daB_end
	global_load_lds_dwordx4 v128, s[92:93]
	s_branch .Lattn_daB_end
.LBB0_372:
	s_add_i32 m0, s75, 0x4400
	s_and_b64 vcc, exec, s[50:51]
	s_cbranch_vccnz .Lattn_daB_end
	global_load_lds_dwordx4 v128, s[94:95]
.Lattn_daB_end:
	ds_read_b128 v[220:223], v135 offset:17440
	ds_read_b128 v[224:227], v139 offset:1024
	s_waitcnt lgkmcnt(5)
	v_mfma_f32_32x32x16_bf16 v[0:15], v[80:83], v[64:67], v[0:15]
	v_fma_f32 v64, v94, s6, -v249
	v_exp_f32_e32 v211, v64
	v_fma_f32 v64, v95, s6, -v249
	s_waitcnt lgkmcnt(3)
	v_mfma_f32_32x32x16_bf16 v[80:95], v[68:71], v[216:219], 0
	ds_read_b128 v[228:231], v135 offset:26144
	v_exp_f32_e32 v212, v64
	v_cvt_pk_bf16_f32 v114, v180, v181
	v_cvt_pk_bf16_f32 v115, v182, v183
	v_cvt_pk_bf16_f32 v116, v122, v123
	v_cvt_pk_bf16_f32 v117, v124, v125
	v_cvt_pk_bf16_f32 v110, v184, v185
	v_cvt_pk_bf16_f32 v111, v205, v206
	v_cvt_pk_bf16_f32 v112, v118, v119
	v_cvt_pk_bf16_f32 v113, v120, v121
	v_cvt_pk_bf16_f32 v106, v207, v208
	v_cvt_pk_bf16_f32 v107, v209, v210
	v_cvt_pk_bf16_f32 v108, v211, v212
	v_fma_f32 v64, v96, s6, -v249
	v_exp_f32_e32 v213, v64
	v_fma_f32 v64, v97, s6, -v249
	v_exp_f32_e32 v214, v64
	v_add_f32_e32 v122, v122, v126
	v_add_f32_e32 v122, v123, v122
	v_add_f32_e32 v122, v124, v122
	s_waitcnt lgkmcnt(3)
	v_mfma_f32_32x32x16_bf16 v[64:79], v[72:75], v[216:219], 0
	ds_read_b128 v[232:235], v135 offset:17472
	ds_read_b128 v[236:239], v139 offset:2048
	v_cvt_pk_bf16_f32 v109, v213, v214
	v_add_f32_e32 v122, v125, v122
	v_add_f32_e32 v122, v184, v122
	v_add_f32_e32 v122, v185, v122
	s_waitcnt lgkmcnt(3)
	v_mfma_f32_32x32x16_bf16 v[80:95], v[220:223], v[224:227], v[80:95]
	v_fma_f32 v96, v98, s6, -v249
	ds_read_b128 v[240:243], v135 offset:26176
	v_exp_f32_e32 v215, v96
	v_add_f32_e32 v122, v205, v122
	v_add_f32_e32 v122, v206, v122
	v_add_f32_e32 v118, v118, v122
	s_waitcnt lgkmcnt(3)
	v_mfma_f32_32x32x16_bf16 v[64:79], v[228:231], v[224:227], v[64:79]
	ds_read_b128 v[218:221], v135 offset:17504
	ds_read_b128 v[244:247], v139 offset:3072
	v_fma_f32 v96, v99, s6, -v249
	v_exp_f32_e32 v216, v96
	v_add_f32_e32 v118, v119, v118
	v_cvt_pk_bf16_f32 v96, v215, v216
	v_add_f32_e32 v118, v120, v118
	v_add_f32_e32 v118, v121, v118
	s_waitcnt lgkmcnt(3)
	v_mfma_f32_32x32x16_bf16 v[80:95], v[232:235], v[236:239], v[80:95]
	v_fma_f32 v97, v100, s6, -v249
	v_exp_f32_e32 v217, v97
	v_fma_f32 v97, v101, s6, -v249
	ds_read_b128 v[222:225], v135 offset:26208
	v_exp_f32_e32 v101, v97
	v_add_f32_e32 v118, v207, v118
	v_cvt_pk_bf16_f32 v97, v217, v101
	v_add_f32_e32 v118, v208, v118
	v_add_f32_e32 v118, v209, v118
	s_waitcnt lgkmcnt(3)
	v_mfma_f32_32x32x16_bf16 v[64:79], v[240:243], v[236:239], v[64:79]
	v_fma_f32 v98, v102, s6, -v249
	v_exp_f32_e32 v102, v98
	v_add_f32_e32 v118, v210, v118
	v_add_f32_e32 v118, v211, v118
	v_add_f32_e32 v118, v212, v118
	s_waitcnt lgkmcnt(1)
	v_mfma_f32_32x32x16_bf16 v[80:95], v[218:221], v[244:247], v[80:95]
	v_fma_f32 v98, v103, s6, -v249
	v_exp_f32_e32 v103, v98
	v_add_f32_e32 v118, v213, v118
	v_cvt_pk_bf16_f32 v98, v102, v103
	v_add_f32_e32 v118, v214, v118
	v_add_f32_e32 v118, v215, v118
	s_waitcnt lgkmcnt(0)
	v_mfma_f32_32x32x16_bf16 v[64:79], v[222:225], v[244:247], v[64:79]
	v_fma_f32 v99, v104, s6, -v249
	v_exp_f32_e32 v104, v99
	v_fma_f32 v99, v105, s6, -v249
	v_exp_f32_e32 v105, v99
	v_exp_f32_e32 v100, v248
	v_cvt_pk_bf16_f32 v99, v104, v105
	v_max3_f32 v218, v80, v81, v82
	v_max3_f32 v218, v218, v83, v84
	v_max3_f32 v218, v218, v85, v86
	v_max3_f32 v218, v218, v87, v88
	v_max3_f32 v218, v218, v89, v90
	v_max3_f32 v218, v218, v91, v92
	v_max3_f32 v218, v218, v93, v94
	v_max3_f32 v218, v218, v95, v64
	v_max3_f32 v218, v218, v65, v66
	v_max3_f32 v218, v218, v67, v68
	v_max3_f32 v218, v218, v69, v70
	v_max3_f32 v218, v218, v71, v72
	v_max3_f32 v218, v218, v73, v74
	v_max3_f32 v218, v218, v75, v76
	v_max3_f32 v218, v218, v77, v78
	v_max_f32_e32 v218, v218, v79
	ds_bpermute_b32 v219, v140, v218
	v_cmp_gt_f32_e32 vcc, 1.0, v100
	s_cbranch_vccz .LBB0_302
	v_pk_mul_f32 v[62:63], v[100:101], v[62:63] op_sel_hi:[0,1]
	v_pk_mul_f32 v[60:61], v[100:101], v[60:61] op_sel_hi:[0,1]
	v_pk_mul_f32 v[58:59], v[100:101], v[58:59] op_sel_hi:[0,1]
	v_pk_mul_f32 v[56:57], v[100:101], v[56:57] op_sel_hi:[0,1]
	v_pk_mul_f32 v[54:55], v[100:101], v[54:55] op_sel_hi:[0,1]
	v_pk_mul_f32 v[52:53], v[100:101], v[52:53] op_sel_hi:[0,1]
	v_pk_mul_f32 v[50:51], v[100:101], v[50:51] op_sel_hi:[0,1]
	v_pk_mul_f32 v[48:49], v[100:101], v[48:49] op_sel_hi:[0,1]
	v_pk_mul_f32 v[46:47], v[100:101], v[46:47] op_sel_hi:[0,1]
	v_pk_mul_f32 v[44:45], v[100:101], v[44:45] op_sel_hi:[0,1]
	v_pk_mul_f32 v[42:43], v[100:101], v[42:43] op_sel_hi:[0,1]
	v_pk_mul_f32 v[40:41], v[100:101], v[40:41] op_sel_hi:[0,1]
	v_pk_mul_f32 v[38:39], v[100:101], v[38:39] op_sel_hi:[0,1]
	v_pk_mul_f32 v[36:37], v[100:101], v[36:37] op_sel_hi:[0,1]
	v_pk_mul_f32 v[34:35], v[100:101], v[34:35] op_sel_hi:[0,1]
	v_pk_mul_f32 v[32:33], v[100:101], v[32:33] op_sel_hi:[0,1]
	v_pk_mul_f32 v[30:31], v[100:101], v[30:31] op_sel_hi:[0,1]
	v_pk_mul_f32 v[28:29], v[100:101], v[28:29] op_sel_hi:[0,1]
	v_pk_mul_f32 v[26:27], v[100:101], v[26:27] op_sel_hi:[0,1]
	v_pk_mul_f32 v[24:25], v[100:101], v[24:25] op_sel_hi:[0,1]
	v_pk_mul_f32 v[22:23], v[100:101], v[22:23] op_sel_hi:[0,1]
	v_pk_mul_f32 v[20:21], v[100:101], v[20:21] op_sel_hi:[0,1]
	v_pk_mul_f32 v[18:19], v[100:101], v[18:19] op_sel_hi:[0,1]
	v_pk_mul_f32 v[16:17], v[100:101], v[16:17] op_sel_hi:[0,1]
	v_pk_mul_f32 v[14:15], v[100:101], v[14:15] op_sel_hi:[0,1]
	v_pk_mul_f32 v[12:13], v[100:101], v[12:13] op_sel_hi:[0,1]
	v_pk_mul_f32 v[10:11], v[100:101], v[10:11] op_sel_hi:[0,1]
	v_pk_mul_f32 v[8:9], v[100:101], v[8:9] op_sel_hi:[0,1]
	v_pk_mul_f32 v[6:7], v[100:101], v[6:7] op_sel_hi:[0,1]
	v_pk_mul_f32 v[4:5], v[100:101], v[4:5] op_sel_hi:[0,1]
	v_pk_mul_f32 v[2:3], v[100:101], v[2:3] op_sel_hi:[0,1]
	v_pk_mul_f32 v[0:1], v[100:101], v[0:1] op_sel_hi:[0,1]
	s_branch .LBB0_302
